# v75 + dec memattn2 loop-head vmcnt(0) (drain of dec_mlstm's trailing stores) removed, both groups
# baseline (speedup 1.0000x reference)
.LBB0_554:
	v_mov_b32_e32 v1, v0
	s_nop 0
	v_readfirstlane_b32 s2, v1
	s_ashr_i32 s47, s2, 6
	s_lshl_b32 s22, s47, 5
	s_ashr_i32 s23, s22, 31
	v_and_b32_e32 v132, 63, v1
	s_lshl_b64 s[2:3], s[22:23], 11
	v_lshl_or_b32 v106, v132, 4, s2
	s_add_u32 s2, s20, s6
	v_lshlrev_b32_e32 v2, 3, v132
	v_mov_b32_e32 v107, s3
	s_addc_u32 s3, s21, s7
	global_load_dwordx2 v[108:109], v2, s[10:11]
	v_lshl_add_u64 v[2:3], s[2:3], 0, v[106:107]
	v_add_co_u32_e32 v4, vcc, s28, v2
	global_load_dwordx4 v[138:141], v[2:3], off nt
	global_load_dwordx4 v[98:101], v[2:3], off offset:2048 nt
	v_addc_co_u32_e32 v5, vcc, 0, v3, vcc
	v_add_co_u32_e32 v102, vcc, s29, v2
	v_addc_co_u32_e32 v103, vcc, 0, v3, vcc
	v_add_co_u32_e32 v6, vcc, s30, v2
	global_load_dwordx4 v[90:93], v[102:103], off nt
	global_load_dwordx4 v[86:89], v[102:103], off offset:2048 nt
	v_addc_co_u32_e32 v7, vcc, 0, v3, vcc
	v_add_co_u32_e32 v8, vcc, s31, v2
	s_nop 0
	v_addc_co_u32_e32 v9, vcc, 0, v3, vcc
	global_load_dwordx4 v[94:97], v[4:5], off offset:2048 nt
	global_load_dwordx4 v[78:81], v[6:7], off offset:2048 nt
	global_load_dwordx4 v[82:85], v[8:9], off offset:-4096 nt
	global_load_dwordx4 v[74:77], v[8:9], off nt
	v_add_co_u32_e32 v4, vcc, s33, v2
	s_nop 0
	v_addc_co_u32_e32 v5, vcc, 0, v3, vcc
	v_add_co_u32_e32 v6, vcc, s36, v2
	s_nop 0
	v_addc_co_u32_e32 v7, vcc, 0, v3, vcc
	global_load_dwordx4 v[66:69], v[8:9], off offset:2048 nt
	global_load_dwordx4 v[62:65], v[6:7], off offset:-4096 nt
	global_load_dwordx4 v[54:57], v[6:7], off nt
	global_load_dwordx4 v[50:53], v[6:7], off offset:2048 nt
	v_add_co_u32_e32 v6, vcc, s37, v2
	s_nop 1
	v_addc_co_u32_e32 v7, vcc, 0, v3, vcc
	v_add_co_u32_e32 v8, vcc, s38, v2
	s_nop 1
	v_addc_co_u32_e32 v9, vcc, 0, v3, vcc
	global_load_dwordx4 v[58:61], v[4:5], off offset:2048 nt
	global_load_dwordx4 v[42:45], v[6:7], off offset:2048 nt
	global_load_dwordx4 v[46:49], v[8:9], off offset:-4096 nt
	global_load_dwordx4 v[126:129], v[8:9], off nt
	v_add_co_u32_e32 v4, vcc, s39, v2
	s_nop 1
	v_addc_co_u32_e32 v5, vcc, 0, v3, vcc
	v_add_co_u32_e32 v6, vcc, s40, v2
	s_nop 1
	v_addc_co_u32_e32 v7, vcc, 0, v3, vcc
	global_load_dwordx4 v[122:125], v[8:9], off offset:2048 nt
	global_load_dwordx4 v[118:121], v[6:7], off offset:-4096 nt
	global_load_dwordx4 v[110:113], v[6:7], off nt
	global_load_dwordx4 v[70:73], v[6:7], off offset:2048 nt
	v_add_co_u32_e32 v6, vcc, s41, v2
	s_nop 1
	v_addc_co_u32_e32 v7, vcc, 0, v3, vcc
	v_add_co_u32_e32 v8, vcc, s42, v2
	s_nop 1
	v_addc_co_u32_e32 v9, vcc, 0, v3, vcc
	global_load_dwordx4 v[114:117], v[4:5], off offset:2048 nt
	global_load_dwordx4 v[34:37], v[6:7], off offset:2048 nt
	global_load_dwordx4 v[38:41], v[8:9], off offset:-4096 nt
	global_load_dwordx4 v[30:33], v[8:9], off nt
	v_add_co_u32_e32 v4, vcc, s43, v2
	s_nop 1
	v_addc_co_u32_e32 v5, vcc, 0, v3, vcc
	v_add_co_u32_e32 v6, vcc, s44, v2
	s_nop 1
	v_addc_co_u32_e32 v7, vcc, 0, v3, vcc
	v_add_co_u32_e32 v2, vcc, s45, v2
	global_load_dwordx4 v[26:29], v[8:9], off offset:2048 nt
	global_load_dwordx4 v[22:25], v[6:7], off offset:-4096 nt
	global_load_dwordx4 v[14:17], v[6:7], off nt
	global_load_dwordx4 v[10:13], v[6:7], off offset:2048 nt
	v_addc_co_u32_e32 v3, vcc, 0, v3, vcc
	global_load_dwordx4 v[18:21], v[4:5], off offset:2048 nt
	global_load_dwordx4 v[6:9], v[2:3], off nt
	s_nop 0
	global_load_dwordx4 v[102:105], v[102:103], off offset:-4096 nt
	s_nop 0
	global_load_dwordx4 v[2:5], v[2:3], off offset:2048 nt
	s_waitcnt vmcnt(32)
	v_lshlrev_b32_e32 v135, 16, v108
	v_and_b32_e32 v137, 0xffff0000, v108
	v_lshlrev_b32_e32 v136, 16, v109
	v_and_b32_e32 v134, 0xffff0000, v109
	v_and_b32_e32 v108, 31, v1
	v_cmp_eq_u32_e64 s[2:3], 0, v108
	v_lshlrev_b32_e32 v108, 5, v1
	v_and_b32_e32 v133, 0x400, v108
	s_waitcnt vmcnt(31)
	v_mul_f32_e32 v108, v139, v137
	v_fmac_f32_e32 v108, v138, v135
	v_fmac_f32_e32 v108, v140, v136
	v_fmac_f32_e32 v108, v141, v134
	s_lshl_b32 s23, s47, 7
	s_add_i32 s23, s23, 0
	v_add_f32_dpp v108, v108, v108 quad_perm:[1,0,3,2] row_mask:0xf bank_mask:0xf bound_ctrl:1
	v_add_u32_e32 v138, s23, v133
	s_nop 0
	v_add_f32_dpp v108, v108, v108 quad_perm:[2,3,0,1] row_mask:0xf bank_mask:0xf bound_ctrl:1
	s_nop 1
	v_add_f32_dpp v108, v108, v108 row_ror:4 row_mask:0xf bank_mask:0xf bound_ctrl:1
	s_nop 1
	v_add_f32_dpp v108, v108, v108 row_ror:8 row_mask:0xf bank_mask:0xf bound_ctrl:1
	v_mov_b32_e32 v109, v108
	s_nop 1
	v_permlane16_swap_b32_e32 v108, v109
	s_and_saveexec_b64 s[24:25], s[2:3]
	v_add_f32_e32 v108, v108, v109
	ds_write_b32 v138, v108
	s_or_b64 exec, exec, s[24:25]
	s_waitcnt vmcnt(30)
	v_mul_f32_e32 v99, v99, v137
	v_fmac_f32_e32 v99, v98, v135
	v_fmac_f32_e32 v99, v100, v136
	v_fmac_f32_e32 v99, v101, v134
	s_nop 1
	v_add_f32_dpp v98, v99, v99 quad_perm:[1,0,3,2] row_mask:0xf bank_mask:0xf bound_ctrl:1
	s_nop 1
	v_add_f32_dpp v98, v98, v98 quad_perm:[2,3,0,1] row_mask:0xf bank_mask:0xf bound_ctrl:1
	s_nop 1
	v_add_f32_dpp v98, v98, v98 row_ror:4 row_mask:0xf bank_mask:0xf bound_ctrl:1
	s_nop 1
	v_add_f32_dpp v98, v98, v98 row_ror:8 row_mask:0xf bank_mask:0xf bound_ctrl:1
	v_mov_b32_e32 v99, v98
	s_nop 1
	v_permlane16_swap_b32_e32 v98, v99
	s_and_saveexec_b64 s[24:25], s[2:3]
	v_add_f32_e32 v98, v98, v99
	ds_write_b32 v138, v98 offset:4
	s_or_b64 exec, exec, s[24:25]
	s_waitcnt vmcnt(1)
	v_mul_f32_e32 v98, v103, v137
	v_fmac_f32_e32 v98, v102, v135
	v_fmac_f32_e32 v98, v104, v136
	v_fmac_f32_e32 v98, v105, v134
	s_nop 1
	v_add_f32_dpp v98, v98, v98 quad_perm:[1,0,3,2] row_mask:0xf bank_mask:0xf bound_ctrl:1
	s_nop 1
	v_add_f32_dpp v98, v98, v98 quad_perm:[2,3,0,1] row_mask:0xf bank_mask:0xf bound_ctrl:1
	s_nop 1
	v_add_f32_dpp v98, v98, v98 row_ror:4 row_mask:0xf bank_mask:0xf bound_ctrl:1
	s_nop 1
	v_add_f32_dpp v98, v98, v98 row_ror:8 row_mask:0xf bank_mask:0xf bound_ctrl:1
	v_mov_b32_e32 v99, v98
	s_nop 1
	v_permlane16_swap_b32_e32 v98, v99
	s_and_saveexec_b64 s[24:25], s[2:3]
	v_add_f32_e32 v98, v98, v99
	ds_write_b32 v138, v98 offset:8
	s_or_b64 exec, exec, s[24:25]
	v_mul_f32_e32 v95, v95, v137
	v_fmac_f32_e32 v95, v94, v135
	v_fmac_f32_e32 v95, v96, v136
	v_fmac_f32_e32 v95, v97, v134
	s_nop 1
	v_add_f32_dpp v94, v95, v95 quad_perm:[1,0,3,2] row_mask:0xf bank_mask:0xf bound_ctrl:1
	s_nop 1
	v_add_f32_dpp v94, v94, v94 quad_perm:[2,3,0,1] row_mask:0xf bank_mask:0xf bound_ctrl:1
	s_nop 1
	v_add_f32_dpp v94, v94, v94 row_ror:4 row_mask:0xf bank_mask:0xf bound_ctrl:1
	s_nop 1
	v_add_f32_dpp v94, v94, v94 row_ror:8 row_mask:0xf bank_mask:0xf bound_ctrl:1
	v_mov_b32_e32 v95, v94
	s_nop 1
	v_permlane16_swap_b32_e32 v94, v95
	s_and_saveexec_b64 s[24:25], s[2:3]
	v_add_f32_e32 v94, v94, v95
	ds_write_b32 v138, v94 offset:12
	s_or_b64 exec, exec, s[24:25]
	v_mul_f32_e32 v91, v91, v137
	v_fmac_f32_e32 v91, v90, v135
	v_fmac_f32_e32 v91, v92, v136
	v_fmac_f32_e32 v91, v93, v134
	s_nop 1
	v_add_f32_dpp v90, v91, v91 quad_perm:[1,0,3,2] row_mask:0xf bank_mask:0xf bound_ctrl:1
	s_nop 1
	v_add_f32_dpp v90, v90, v90 quad_perm:[2,3,0,1] row_mask:0xf bank_mask:0xf bound_ctrl:1
	s_nop 1
	v_add_f32_dpp v90, v90, v90 row_ror:4 row_mask:0xf bank_mask:0xf bound_ctrl:1
	s_nop 1
	v_add_f32_dpp v90, v90, v90 row_ror:8 row_mask:0xf bank_mask:0xf bound_ctrl:1
	v_mov_b32_e32 v91, v90
	s_nop 1
	v_permlane16_swap_b32_e32 v90, v91
	s_and_saveexec_b64 s[24:25], s[2:3]
	v_add_f32_e32 v90, v90, v91
	ds_write_b32 v138, v90 offset:16
	s_or_b64 exec, exec, s[24:25]
	v_mul_f32_e32 v87, v87, v137
	v_fmac_f32_e32 v87, v86, v135
	v_fmac_f32_e32 v87, v88, v136
	v_fmac_f32_e32 v87, v89, v134
	s_nop 1
	v_add_f32_dpp v86, v87, v87 quad_perm:[1,0,3,2] row_mask:0xf bank_mask:0xf bound_ctrl:1
	s_nop 1
	v_add_f32_dpp v86, v86, v86 quad_perm:[2,3,0,1] row_mask:0xf bank_mask:0xf bound_ctrl:1
	s_nop 1
	v_add_f32_dpp v86, v86, v86 row_ror:4 row_mask:0xf bank_mask:0xf bound_ctrl:1
	s_nop 1
	v_add_f32_dpp v86, v86, v86 row_ror:8 row_mask:0xf bank_mask:0xf bound_ctrl:1
	v_mov_b32_e32 v87, v86
	s_nop 1
	v_permlane16_swap_b32_e32 v86, v87
	s_and_saveexec_b64 s[24:25], s[2:3]
	v_add_f32_e32 v86, v86, v87
	ds_write_b32 v138, v86 offset:20
	s_or_b64 exec, exec, s[24:25]
	v_mul_f32_e32 v83, v83, v137
	v_fmac_f32_e32 v83, v82, v135
	v_fmac_f32_e32 v83, v84, v136
	v_fmac_f32_e32 v83, v85, v134
	s_nop 1
	v_add_f32_dpp v82, v83, v83 quad_perm:[1,0,3,2] row_mask:0xf bank_mask:0xf bound_ctrl:1
	s_nop 1
	v_add_f32_dpp v82, v82, v82 quad_perm:[2,3,0,1] row_mask:0xf bank_mask:0xf bound_ctrl:1
	s_nop 1
	v_add_f32_dpp v82, v82, v82 row_ror:4 row_mask:0xf bank_mask:0xf bound_ctrl:1
	s_nop 1
	v_add_f32_dpp v82, v82, v82 row_ror:8 row_mask:0xf bank_mask:0xf bound_ctrl:1
	v_mov_b32_e32 v83, v82
	s_nop 1
	v_permlane16_swap_b32_e32 v82, v83
	s_and_saveexec_b64 s[24:25], s[2:3]
	v_add_f32_e32 v82, v82, v83
	ds_write_b32 v138, v82 offset:24
	s_or_b64 exec, exec, s[24:25]
	v_mul_f32_e32 v79, v79, v137
	v_fmac_f32_e32 v79, v78, v135
	v_fmac_f32_e32 v79, v80, v136
	v_fmac_f32_e32 v79, v81, v134
	s_nop 1
	v_add_f32_dpp v78, v79, v79 quad_perm:[1,0,3,2] row_mask:0xf bank_mask:0xf bound_ctrl:1
	s_nop 1
	v_add_f32_dpp v78, v78, v78 quad_perm:[2,3,0,1] row_mask:0xf bank_mask:0xf bound_ctrl:1
	s_nop 1
	v_add_f32_dpp v78, v78, v78 row_ror:4 row_mask:0xf bank_mask:0xf bound_ctrl:1
	s_nop 1
	v_add_f32_dpp v78, v78, v78 row_ror:8 row_mask:0xf bank_mask:0xf bound_ctrl:1
	v_mov_b32_e32 v79, v78
	s_nop 1
	v_permlane16_swap_b32_e32 v78, v79
	s_and_saveexec_b64 s[24:25], s[2:3]
	v_add_f32_e32 v78, v78, v79
	ds_write_b32 v138, v78 offset:28
	s_or_b64 exec, exec, s[24:25]
	v_mul_f32_e32 v75, v75, v137
	v_fmac_f32_e32 v75, v74, v135
	v_fmac_f32_e32 v75, v76, v136
	v_fmac_f32_e32 v75, v77, v134
	s_nop 1
	v_add_f32_dpp v74, v75, v75 quad_perm:[1,0,3,2] row_mask:0xf bank_mask:0xf bound_ctrl:1
	s_nop 1
	v_add_f32_dpp v74, v74, v74 quad_perm:[2,3,0,1] row_mask:0xf bank_mask:0xf bound_ctrl:1
	s_nop 1
	v_add_f32_dpp v74, v74, v74 row_ror:4 row_mask:0xf bank_mask:0xf bound_ctrl:1
	s_nop 1
	v_add_f32_dpp v74, v74, v74 row_ror:8 row_mask:0xf bank_mask:0xf bound_ctrl:1
	v_mov_b32_e32 v75, v74
	s_nop 1
	v_permlane16_swap_b32_e32 v74, v75
	s_and_saveexec_b64 s[24:25], s[2:3]
	v_add_f32_e32 v74, v74, v75
	ds_write_b32 v138, v74 offset:32
	s_or_b64 exec, exec, s[24:25]
	v_mul_f32_e32 v67, v67, v137
	v_fmac_f32_e32 v67, v66, v135
	v_fmac_f32_e32 v67, v68, v136
	v_fmac_f32_e32 v67, v69, v134
	s_nop 1
	v_add_f32_dpp v66, v67, v67 quad_perm:[1,0,3,2] row_mask:0xf bank_mask:0xf bound_ctrl:1
	s_nop 1
	v_add_f32_dpp v66, v66, v66 quad_perm:[2,3,0,1] row_mask:0xf bank_mask:0xf bound_ctrl:1
	s_nop 1
	v_add_f32_dpp v66, v66, v66 row_ror:4 row_mask:0xf bank_mask:0xf bound_ctrl:1
	s_nop 1
	v_add_f32_dpp v66, v66, v66 row_ror:8 row_mask:0xf bank_mask:0xf bound_ctrl:1
	v_mov_b32_e32 v67, v66
	s_nop 1
	v_permlane16_swap_b32_e32 v66, v67
	s_and_saveexec_b64 s[24:25], s[2:3]
	v_add_f32_e32 v66, v66, v67
	ds_write_b32 v138, v66 offset:36
	s_or_b64 exec, exec, s[24:25]
	v_mul_f32_e32 v63, v63, v137
	v_fmac_f32_e32 v63, v62, v135
	v_fmac_f32_e32 v63, v64, v136
	v_fmac_f32_e32 v63, v65, v134
	s_nop 1
	v_add_f32_dpp v62, v63, v63 quad_perm:[1,0,3,2] row_mask:0xf bank_mask:0xf bound_ctrl:1
	s_nop 1
	v_add_f32_dpp v62, v62, v62 quad_perm:[2,3,0,1] row_mask:0xf bank_mask:0xf bound_ctrl:1
	s_nop 1
	v_add_f32_dpp v62, v62, v62 row_ror:4 row_mask:0xf bank_mask:0xf bound_ctrl:1
	s_nop 1
	v_add_f32_dpp v62, v62, v62 row_ror:8 row_mask:0xf bank_mask:0xf bound_ctrl:1
	v_mov_b32_e32 v63, v62
	s_nop 1
	v_permlane16_swap_b32_e32 v62, v63
	s_and_saveexec_b64 s[24:25], s[2:3]
	v_add_f32_e32 v62, v62, v63
	ds_write_b32 v138, v62 offset:40
	s_or_b64 exec, exec, s[24:25]
	v_mul_f32_e32 v59, v59, v137
	v_fmac_f32_e32 v59, v58, v135
	v_fmac_f32_e32 v59, v60, v136
	v_fmac_f32_e32 v59, v61, v134
	s_nop 1
	v_add_f32_dpp v58, v59, v59 quad_perm:[1,0,3,2] row_mask:0xf bank_mask:0xf bound_ctrl:1
	s_nop 1
	v_add_f32_dpp v58, v58, v58 quad_perm:[2,3,0,1] row_mask:0xf bank_mask:0xf bound_ctrl:1
	s_nop 1
	v_add_f32_dpp v58, v58, v58 row_ror:4 row_mask:0xf bank_mask:0xf bound_ctrl:1
	s_nop 1
	v_add_f32_dpp v58, v58, v58 row_ror:8 row_mask:0xf bank_mask:0xf bound_ctrl:1
	v_mov_b32_e32 v59, v58
	s_nop 1
	v_permlane16_swap_b32_e32 v58, v59
	s_and_saveexec_b64 s[24:25], s[2:3]
	v_add_f32_e32 v58, v58, v59
	ds_write_b32 v138, v58 offset:44
	s_or_b64 exec, exec, s[24:25]
	v_mul_f32_e32 v55, v55, v137
	v_fmac_f32_e32 v55, v54, v135
	v_fmac_f32_e32 v55, v56, v136
	v_fmac_f32_e32 v55, v57, v134
	s_nop 1
	v_add_f32_dpp v54, v55, v55 quad_perm:[1,0,3,2] row_mask:0xf bank_mask:0xf bound_ctrl:1
	s_nop 1
	v_add_f32_dpp v54, v54, v54 quad_perm:[2,3,0,1] row_mask:0xf bank_mask:0xf bound_ctrl:1
	s_nop 1
	v_add_f32_dpp v54, v54, v54 row_ror:4 row_mask:0xf bank_mask:0xf bound_ctrl:1
	s_nop 1
	v_add_f32_dpp v54, v54, v54 row_ror:8 row_mask:0xf bank_mask:0xf bound_ctrl:1
	v_mov_b32_e32 v55, v54
	s_nop 1
	v_permlane16_swap_b32_e32 v54, v55
	s_and_saveexec_b64 s[24:25], s[2:3]
	v_add_f32_e32 v54, v54, v55
	ds_write_b32 v138, v54 offset:48
	s_or_b64 exec, exec, s[24:25]
	v_mul_f32_e32 v51, v51, v137
	v_fmac_f32_e32 v51, v50, v135
	v_fmac_f32_e32 v51, v52, v136
	v_fmac_f32_e32 v51, v53, v134
	s_nop 1
	v_add_f32_dpp v50, v51, v51 quad_perm:[1,0,3,2] row_mask:0xf bank_mask:0xf bound_ctrl:1
	s_nop 1
	v_add_f32_dpp v50, v50, v50 quad_perm:[2,3,0,1] row_mask:0xf bank_mask:0xf bound_ctrl:1
	s_nop 1
	v_add_f32_dpp v50, v50, v50 row_ror:4 row_mask:0xf bank_mask:0xf bound_ctrl:1
	s_nop 1
	v_add_f32_dpp v50, v50, v50 row_ror:8 row_mask:0xf bank_mask:0xf bound_ctrl:1
	v_mov_b32_e32 v51, v50
	s_nop 1
	v_permlane16_swap_b32_e32 v50, v51
	s_and_saveexec_b64 s[24:25], s[2:3]
	v_add_f32_e32 v50, v50, v51
	ds_write_b32 v138, v50 offset:52
	s_or_b64 exec, exec, s[24:25]
	v_mul_f32_e32 v47, v47, v137
	v_fmac_f32_e32 v47, v46, v135
	v_fmac_f32_e32 v47, v48, v136
	v_fmac_f32_e32 v47, v49, v134
	s_nop 1
	v_add_f32_dpp v46, v47, v47 quad_perm:[1,0,3,2] row_mask:0xf bank_mask:0xf bound_ctrl:1
	s_nop 1
	v_add_f32_dpp v46, v46, v46 quad_perm:[2,3,0,1] row_mask:0xf bank_mask:0xf bound_ctrl:1
	s_nop 1
	v_add_f32_dpp v46, v46, v46 row_ror:4 row_mask:0xf bank_mask:0xf bound_ctrl:1
	s_nop 1
	v_add_f32_dpp v46, v46, v46 row_ror:8 row_mask:0xf bank_mask:0xf bound_ctrl:1
	v_mov_b32_e32 v47, v46
	s_nop 1
	v_permlane16_swap_b32_e32 v46, v47
	s_and_saveexec_b64 s[24:25], s[2:3]
	v_add_f32_e32 v46, v46, v47
	ds_write_b32 v138, v46 offset:56
	s_or_b64 exec, exec, s[24:25]
	v_mul_f32_e32 v43, v43, v137
	v_fmac_f32_e32 v43, v42, v135
	v_fmac_f32_e32 v43, v44, v136
	v_fmac_f32_e32 v43, v45, v134
	s_nop 1
	v_add_f32_dpp v42, v43, v43 quad_perm:[1,0,3,2] row_mask:0xf bank_mask:0xf bound_ctrl:1
	s_nop 1
	v_add_f32_dpp v42, v42, v42 quad_perm:[2,3,0,1] row_mask:0xf bank_mask:0xf bound_ctrl:1
	s_nop 1
	v_add_f32_dpp v42, v42, v42 row_ror:4 row_mask:0xf bank_mask:0xf bound_ctrl:1
	s_nop 1
	v_add_f32_dpp v42, v42, v42 row_ror:8 row_mask:0xf bank_mask:0xf bound_ctrl:1
	v_mov_b32_e32 v43, v42
	s_nop 1
	v_permlane16_swap_b32_e32 v42, v43
	s_and_saveexec_b64 s[24:25], s[2:3]
	v_add_f32_e32 v42, v42, v43
	ds_write_b32 v138, v42 offset:60
	s_or_b64 exec, exec, s[24:25]
	s_add_u32 s24, s18, s6
	s_addc_u32 s25, s19, s7
	v_lshl_add_u64 v[130:131], s[24:25], 0, v[106:107]
	v_add_co_u32_e32 v42, vcc, 0x1000, v130
	global_load_dwordx4 v[106:109], v[130:131], off nt
	global_load_dwordx4 v[94:97], v[130:131], off offset:2048 nt
	v_addc_co_u32_e32 v43, vcc, 0, v131, vcc
	global_load_dwordx4 v[102:105], v[42:43], off nt
	global_load_dwordx4 v[78:81], v[42:43], off offset:2048 nt
	v_add_co_u32_e32 v42, vcc, 0x2000, v130
	s_nop 1
	v_addc_co_u32_e32 v43, vcc, 0, v131, vcc
	global_load_dwordx4 v[98:101], v[42:43], off nt
	global_load_dwordx4 v[82:85], v[42:43], off offset:2048 nt
	v_add_co_u32_e32 v42, vcc, 0x3000, v130
	s_nop 1
	v_addc_co_u32_e32 v43, vcc, 0, v131, vcc
	global_load_dwordx4 v[90:93], v[42:43], off nt
	global_load_dwordx4 v[58:61], v[42:43], off offset:2048 nt
	v_add_co_u32_e32 v42, vcc, 0x4000, v130
	s_nop 1
	v_addc_co_u32_e32 v43, vcc, 0, v131, vcc
	global_load_dwordx4 v[86:89], v[42:43], off nt
	global_load_dwordx4 v[62:65], v[42:43], off offset:2048 nt
	v_add_co_u32_e32 v42, vcc, 0x5000, v130
	s_nop 1
	v_addc_co_u32_e32 v43, vcc, 0, v131, vcc
	global_load_dwordx4 v[74:77], v[42:43], off nt
	global_load_dwordx4 v[46:49], v[42:43], off offset:2048 nt
	v_add_co_u32_e32 v42, vcc, 0x6000, v130
	s_nop 1
	v_addc_co_u32_e32 v43, vcc, 0, v131, vcc
	global_load_dwordx4 v[66:69], v[42:43], off nt
	global_load_dwordx4 v[50:53], v[42:43], off offset:2048 nt
	v_add_co_u32_e32 v42, vcc, 0x7000, v130
	s_nop 1
	v_addc_co_u32_e32 v43, vcc, 0, v131, vcc
	global_load_dwordx4 v[54:57], v[42:43], off nt
	s_nop 0
	global_load_dwordx4 v[42:45], v[42:43], off offset:2048 nt
	v_mul_f32_e32 v127, v127, v137
	v_fmac_f32_e32 v127, v126, v135
	v_fmac_f32_e32 v127, v128, v136
	v_fmac_f32_e32 v127, v129, v134
	s_nop 1
	v_add_f32_dpp v126, v127, v127 quad_perm:[1,0,3,2] row_mask:0xf bank_mask:0xf bound_ctrl:1
	s_nop 1
	v_add_f32_dpp v126, v126, v126 quad_perm:[2,3,0,1] row_mask:0xf bank_mask:0xf bound_ctrl:1
	s_nop 1
	v_add_f32_dpp v126, v126, v126 row_ror:4 row_mask:0xf bank_mask:0xf bound_ctrl:1
	s_nop 1
	v_add_f32_dpp v126, v126, v126 row_ror:8 row_mask:0xf bank_mask:0xf bound_ctrl:1
	v_mov_b32_e32 v127, v126
	s_nop 1
	v_permlane16_swap_b32_e32 v126, v127
	s_and_saveexec_b64 s[24:25], s[2:3]
	v_add_f32_e32 v126, v126, v127
	ds_write_b32 v138, v126 offset:64
	s_or_b64 exec, exec, s[24:25]
	v_mul_f32_e32 v123, v123, v137
	v_fmac_f32_e32 v123, v122, v135
	v_fmac_f32_e32 v123, v124, v136
	v_fmac_f32_e32 v123, v125, v134
	s_nop 1
	v_add_f32_dpp v122, v123, v123 quad_perm:[1,0,3,2] row_mask:0xf bank_mask:0xf bound_ctrl:1
	s_nop 1
	v_add_f32_dpp v122, v122, v122 quad_perm:[2,3,0,1] row_mask:0xf bank_mask:0xf bound_ctrl:1
	s_nop 1
	v_add_f32_dpp v122, v122, v122 row_ror:4 row_mask:0xf bank_mask:0xf bound_ctrl:1
	s_nop 1
	v_add_f32_dpp v122, v122, v122 row_ror:8 row_mask:0xf bank_mask:0xf bound_ctrl:1
	v_mov_b32_e32 v123, v122
	s_nop 1
	v_permlane16_swap_b32_e32 v122, v123
	s_and_saveexec_b64 s[24:25], s[2:3]
	v_add_f32_e32 v122, v122, v123
	ds_write_b32 v138, v122 offset:68
	s_or_b64 exec, exec, s[24:25]
	v_mul_f32_e32 v119, v119, v137
	v_fmac_f32_e32 v119, v118, v135
	v_fmac_f32_e32 v119, v120, v136
	v_fmac_f32_e32 v119, v121, v134
	s_nop 1
	v_add_f32_dpp v118, v119, v119 quad_perm:[1,0,3,2] row_mask:0xf bank_mask:0xf bound_ctrl:1
	s_nop 1
	v_add_f32_dpp v118, v118, v118 quad_perm:[2,3,0,1] row_mask:0xf bank_mask:0xf bound_ctrl:1
	s_nop 1
	v_add_f32_dpp v118, v118, v118 row_ror:4 row_mask:0xf bank_mask:0xf bound_ctrl:1
	s_nop 1
	v_add_f32_dpp v118, v118, v118 row_ror:8 row_mask:0xf bank_mask:0xf bound_ctrl:1
	v_mov_b32_e32 v119, v118
	s_nop 1
	v_permlane16_swap_b32_e32 v118, v119
	s_and_saveexec_b64 s[24:25], s[2:3]
	v_add_f32_e32 v118, v118, v119
	ds_write_b32 v138, v118 offset:72
	s_or_b64 exec, exec, s[24:25]
	v_mul_f32_e32 v115, v115, v137
	v_fmac_f32_e32 v115, v114, v135
	v_fmac_f32_e32 v115, v116, v136
	v_fmac_f32_e32 v115, v117, v134
	s_nop 1
	v_add_f32_dpp v114, v115, v115 quad_perm:[1,0,3,2] row_mask:0xf bank_mask:0xf bound_ctrl:1
	s_nop 1
	v_add_f32_dpp v114, v114, v114 quad_perm:[2,3,0,1] row_mask:0xf bank_mask:0xf bound_ctrl:1
	s_nop 1
	v_add_f32_dpp v114, v114, v114 row_ror:4 row_mask:0xf bank_mask:0xf bound_ctrl:1
	s_nop 1
	v_add_f32_dpp v114, v114, v114 row_ror:8 row_mask:0xf bank_mask:0xf bound_ctrl:1
	v_mov_b32_e32 v115, v114
	s_nop 1
	v_permlane16_swap_b32_e32 v114, v115
	s_and_saveexec_b64 s[24:25], s[2:3]
	v_add_f32_e32 v114, v114, v115
	ds_write_b32 v138, v114 offset:76
	s_or_b64 exec, exec, s[24:25]
	v_mul_f32_e32 v111, v111, v137
	v_fmac_f32_e32 v111, v110, v135
	v_fmac_f32_e32 v111, v112, v136
	v_fmac_f32_e32 v111, v113, v134
	s_nop 1
	v_add_f32_dpp v110, v111, v111 quad_perm:[1,0,3,2] row_mask:0xf bank_mask:0xf bound_ctrl:1
	s_nop 1
	v_add_f32_dpp v110, v110, v110 quad_perm:[2,3,0,1] row_mask:0xf bank_mask:0xf bound_ctrl:1
	s_nop 1
	v_add_f32_dpp v110, v110, v110 row_ror:4 row_mask:0xf bank_mask:0xf bound_ctrl:1
	s_nop 1
	v_add_f32_dpp v110, v110, v110 row_ror:8 row_mask:0xf bank_mask:0xf bound_ctrl:1
	v_mov_b32_e32 v111, v110
	s_nop 1
	v_permlane16_swap_b32_e32 v110, v111
	s_and_saveexec_b64 s[24:25], s[2:3]
	v_add_f32_e32 v110, v110, v111
	ds_write_b32 v138, v110 offset:80
	s_or_b64 exec, exec, s[24:25]
	v_mul_f32_e32 v71, v71, v137
	v_fmac_f32_e32 v71, v70, v135
	v_fmac_f32_e32 v71, v72, v136
	v_fmac_f32_e32 v71, v73, v134
	s_nop 1
	v_add_f32_dpp v70, v71, v71 quad_perm:[1,0,3,2] row_mask:0xf bank_mask:0xf bound_ctrl:1
	s_nop 1
	v_add_f32_dpp v70, v70, v70 quad_perm:[2,3,0,1] row_mask:0xf bank_mask:0xf bound_ctrl:1
	s_nop 1
	v_add_f32_dpp v70, v70, v70 row_ror:4 row_mask:0xf bank_mask:0xf bound_ctrl:1
	s_nop 1
	v_add_f32_dpp v70, v70, v70 row_ror:8 row_mask:0xf bank_mask:0xf bound_ctrl:1
	v_mov_b32_e32 v71, v70
	s_nop 1
	v_permlane16_swap_b32_e32 v70, v71
	s_and_saveexec_b64 s[24:25], s[2:3]
	v_add_f32_e32 v70, v70, v71
	ds_write_b32 v138, v70 offset:84
	s_or_b64 exec, exec, s[24:25]
	v_mul_f32_e32 v39, v39, v137
	v_fmac_f32_e32 v39, v38, v135
	v_fmac_f32_e32 v39, v40, v136
	v_fmac_f32_e32 v39, v41, v134
	s_nop 1
	v_add_f32_dpp v38, v39, v39 quad_perm:[1,0,3,2] row_mask:0xf bank_mask:0xf bound_ctrl:1
	s_nop 1
	v_add_f32_dpp v38, v38, v38 quad_perm:[2,3,0,1] row_mask:0xf bank_mask:0xf bound_ctrl:1
	s_nop 1
	v_add_f32_dpp v38, v38, v38 row_ror:4 row_mask:0xf bank_mask:0xf bound_ctrl:1
	s_nop 1
	v_add_f32_dpp v38, v38, v38 row_ror:8 row_mask:0xf bank_mask:0xf bound_ctrl:1
	v_mov_b32_e32 v39, v38
	s_nop 1
	v_permlane16_swap_b32_e32 v38, v39
	s_and_saveexec_b64 s[24:25], s[2:3]
	v_add_f32_e32 v38, v38, v39
	ds_write_b32 v138, v38 offset:88
	s_or_b64 exec, exec, s[24:25]
	v_mul_f32_e32 v35, v35, v137
	v_fmac_f32_e32 v35, v34, v135
	v_fmac_f32_e32 v35, v36, v136
	v_fmac_f32_e32 v35, v37, v134
	s_nop 1
	v_add_f32_dpp v34, v35, v35 quad_perm:[1,0,3,2] row_mask:0xf bank_mask:0xf bound_ctrl:1
	s_nop 1
	v_add_f32_dpp v34, v34, v34 quad_perm:[2,3,0,1] row_mask:0xf bank_mask:0xf bound_ctrl:1
	s_nop 1
	v_add_f32_dpp v34, v34, v34 row_ror:4 row_mask:0xf bank_mask:0xf bound_ctrl:1
	s_nop 1
	v_add_f32_dpp v34, v34, v34 row_ror:8 row_mask:0xf bank_mask:0xf bound_ctrl:1
	v_mov_b32_e32 v35, v34
	s_nop 1
	v_permlane16_swap_b32_e32 v34, v35
	s_and_saveexec_b64 s[24:25], s[2:3]
	v_add_f32_e32 v34, v34, v35
	ds_write_b32 v138, v34 offset:92
	s_or_b64 exec, exec, s[24:25]
	v_mul_f32_e32 v31, v31, v137
	v_fmac_f32_e32 v31, v30, v135
	v_fmac_f32_e32 v31, v32, v136
	v_fmac_f32_e32 v31, v33, v134
	s_nop 1
	v_add_f32_dpp v30, v31, v31 quad_perm:[1,0,3,2] row_mask:0xf bank_mask:0xf bound_ctrl:1
	s_nop 1
	v_add_f32_dpp v30, v30, v30 quad_perm:[2,3,0,1] row_mask:0xf bank_mask:0xf bound_ctrl:1
	s_nop 1
	v_add_f32_dpp v30, v30, v30 row_ror:4 row_mask:0xf bank_mask:0xf bound_ctrl:1
	s_nop 1
	v_add_f32_dpp v30, v30, v30 row_ror:8 row_mask:0xf bank_mask:0xf bound_ctrl:1
	v_mov_b32_e32 v31, v30
	s_nop 1
	v_permlane16_swap_b32_e32 v30, v31
	s_and_saveexec_b64 s[24:25], s[2:3]
	v_add_f32_e32 v30, v30, v31
	ds_write_b32 v138, v30 offset:96
	s_or_b64 exec, exec, s[24:25]
	v_mul_f32_e32 v27, v27, v137
	v_fmac_f32_e32 v27, v26, v135
	v_fmac_f32_e32 v27, v28, v136
	v_fmac_f32_e32 v27, v29, v134
	s_nop 1
	v_add_f32_dpp v26, v27, v27 quad_perm:[1,0,3,2] row_mask:0xf bank_mask:0xf bound_ctrl:1
	s_nop 1
	v_add_f32_dpp v26, v26, v26 quad_perm:[2,3,0,1] row_mask:0xf bank_mask:0xf bound_ctrl:1
	s_nop 1
	v_add_f32_dpp v26, v26, v26 row_ror:4 row_mask:0xf bank_mask:0xf bound_ctrl:1
	s_nop 1
	v_add_f32_dpp v26, v26, v26 row_ror:8 row_mask:0xf bank_mask:0xf bound_ctrl:1
	v_mov_b32_e32 v27, v26
	s_nop 1
	v_permlane16_swap_b32_e32 v26, v27
	s_and_saveexec_b64 s[24:25], s[2:3]
	v_add_f32_e32 v26, v26, v27
	ds_write_b32 v138, v26 offset:100
	s_or_b64 exec, exec, s[24:25]
	v_mul_f32_e32 v23, v23, v137
	v_fmac_f32_e32 v23, v22, v135
	v_fmac_f32_e32 v23, v24, v136
	v_fmac_f32_e32 v23, v25, v134
	s_nop 1
	v_add_f32_dpp v22, v23, v23 quad_perm:[1,0,3,2] row_mask:0xf bank_mask:0xf bound_ctrl:1
	s_nop 1
	v_add_f32_dpp v22, v22, v22 quad_perm:[2,3,0,1] row_mask:0xf bank_mask:0xf bound_ctrl:1
	s_nop 1
	v_add_f32_dpp v22, v22, v22 row_ror:4 row_mask:0xf bank_mask:0xf bound_ctrl:1
	s_nop 1
	v_add_f32_dpp v22, v22, v22 row_ror:8 row_mask:0xf bank_mask:0xf bound_ctrl:1
	v_mov_b32_e32 v23, v22
	s_nop 1
	v_permlane16_swap_b32_e32 v22, v23
	s_and_saveexec_b64 s[24:25], s[2:3]
	v_add_f32_e32 v22, v22, v23
	ds_write_b32 v138, v22 offset:104
	s_or_b64 exec, exec, s[24:25]
	v_mul_f32_e32 v19, v19, v137
	v_fmac_f32_e32 v19, v18, v135
	v_fmac_f32_e32 v19, v20, v136
	v_fmac_f32_e32 v19, v21, v134
	s_nop 1
	v_add_f32_dpp v18, v19, v19 quad_perm:[1,0,3,2] row_mask:0xf bank_mask:0xf bound_ctrl:1
	s_nop 1
	v_add_f32_dpp v18, v18, v18 quad_perm:[2,3,0,1] row_mask:0xf bank_mask:0xf bound_ctrl:1
	s_nop 1
	v_add_f32_dpp v18, v18, v18 row_ror:4 row_mask:0xf bank_mask:0xf bound_ctrl:1
	s_nop 1
	v_add_f32_dpp v18, v18, v18 row_ror:8 row_mask:0xf bank_mask:0xf bound_ctrl:1
	v_mov_b32_e32 v19, v18
	s_nop 1
	v_permlane16_swap_b32_e32 v18, v19
	s_and_saveexec_b64 s[24:25], s[2:3]
	v_add_f32_e32 v18, v18, v19
	ds_write_b32 v138, v18 offset:108
	s_or_b64 exec, exec, s[24:25]
	v_mul_f32_e32 v15, v15, v137
	v_fmac_f32_e32 v15, v14, v135
	v_fmac_f32_e32 v15, v16, v136
	v_fmac_f32_e32 v15, v17, v134
	s_nop 1
	v_add_f32_dpp v14, v15, v15 quad_perm:[1,0,3,2] row_mask:0xf bank_mask:0xf bound_ctrl:1
	s_nop 1
	v_add_f32_dpp v14, v14, v14 quad_perm:[2,3,0,1] row_mask:0xf bank_mask:0xf bound_ctrl:1
	s_nop 1
	v_add_f32_dpp v14, v14, v14 row_ror:4 row_mask:0xf bank_mask:0xf bound_ctrl:1
	s_nop 1
	v_add_f32_dpp v14, v14, v14 row_ror:8 row_mask:0xf bank_mask:0xf bound_ctrl:1
	v_mov_b32_e32 v15, v14
	s_nop 1
	v_permlane16_swap_b32_e32 v14, v15
	s_and_saveexec_b64 s[24:25], s[2:3]
	v_add_f32_e32 v14, v14, v15
	ds_write_b32 v138, v14 offset:112
	s_or_b64 exec, exec, s[24:25]
	v_mul_f32_e32 v11, v11, v137
	v_fmac_f32_e32 v11, v10, v135
	v_fmac_f32_e32 v11, v12, v136
	v_fmac_f32_e32 v11, v13, v134
	s_nop 1
	v_add_f32_dpp v10, v11, v11 quad_perm:[1,0,3,2] row_mask:0xf bank_mask:0xf bound_ctrl:1
	s_nop 1
	v_add_f32_dpp v10, v10, v10 quad_perm:[2,3,0,1] row_mask:0xf bank_mask:0xf bound_ctrl:1
	s_nop 1
	v_add_f32_dpp v10, v10, v10 row_ror:4 row_mask:0xf bank_mask:0xf bound_ctrl:1
	s_nop 1
	v_add_f32_dpp v10, v10, v10 row_ror:8 row_mask:0xf bank_mask:0xf bound_ctrl:1
	v_mov_b32_e32 v11, v10
	s_nop 1
	v_permlane16_swap_b32_e32 v10, v11
	s_and_saveexec_b64 s[24:25], s[2:3]
	v_add_f32_e32 v10, v10, v11
	ds_write_b32 v138, v10 offset:116
	s_or_b64 exec, exec, s[24:25]
	v_mul_f32_e32 v7, v7, v137
	v_fmac_f32_e32 v7, v6, v135
	v_fmac_f32_e32 v7, v8, v136
	v_fmac_f32_e32 v7, v9, v134
	s_nop 1
	v_add_f32_dpp v6, v7, v7 quad_perm:[1,0,3,2] row_mask:0xf bank_mask:0xf bound_ctrl:1
	s_nop 1
	v_add_f32_dpp v6, v6, v6 quad_perm:[2,3,0,1] row_mask:0xf bank_mask:0xf bound_ctrl:1
	s_nop 1
	v_add_f32_dpp v6, v6, v6 row_ror:4 row_mask:0xf bank_mask:0xf bound_ctrl:1
	s_nop 1
	v_add_f32_dpp v6, v6, v6 row_ror:8 row_mask:0xf bank_mask:0xf bound_ctrl:1
	v_mov_b32_e32 v7, v6
	s_nop 1
	v_permlane16_swap_b32_e32 v6, v7
	s_and_saveexec_b64 s[24:25], s[2:3]
	v_add_f32_e32 v6, v6, v7
	ds_write_b32 v138, v6 offset:120
	s_or_b64 exec, exec, s[24:25]
	s_waitcnt vmcnt(16)
	v_mul_f32_e32 v3, v3, v137
	v_fmac_f32_e32 v3, v2, v135
	v_fmac_f32_e32 v3, v4, v136
	v_fmac_f32_e32 v3, v5, v134
	s_nop 1
	v_add_f32_dpp v2, v3, v3 quad_perm:[1,0,3,2] row_mask:0xf bank_mask:0xf bound_ctrl:1
	s_nop 1
	v_add_f32_dpp v2, v2, v2 quad_perm:[2,3,0,1] row_mask:0xf bank_mask:0xf bound_ctrl:1
	s_nop 1
	v_add_f32_dpp v2, v2, v2 row_ror:4 row_mask:0xf bank_mask:0xf bound_ctrl:1
	s_nop 1
	v_add_f32_dpp v2, v2, v2 row_ror:8 row_mask:0xf bank_mask:0xf bound_ctrl:1
	v_mov_b32_e32 v3, v2
	s_nop 1
	v_permlane16_swap_b32_e32 v2, v3
	s_and_saveexec_b64 s[24:25], s[2:3]
	v_add_f32_e32 v2, v2, v3
	ds_write_b32 v138, v2 offset:124
	s_or_b64 exec, exec, s[24:25]
	v_lshlrev_b32_e32 v134, 2, v132
	v_add_co_u32_e32 v2, vcc, 0x8000, v130
	s_nop 1
	v_addc_co_u32_e32 v3, vcc, 0, v131, vcc
	global_load_dwordx4 v[70:73], v[2:3], off nt
	global_load_dwordx4 v[38:41], v[2:3], off offset:2048 nt
	v_add_co_u32_e32 v2, vcc, 0x9000, v130
	s_nop 1
	v_addc_co_u32_e32 v3, vcc, 0, v131, vcc
	global_load_dwordx4 v[118:121], v[2:3], off nt
	global_load_dwordx4 v[110:113], v[2:3], off offset:2048 nt
	v_add_co_u32_e32 v2, vcc, 0xa000, v130
	s_nop 1
	v_addc_co_u32_e32 v3, vcc, 0, v131, vcc
	global_load_dwordx4 v[126:129], v[2:3], off nt
	global_load_dwordx4 v[114:117], v[2:3], off offset:2048 nt
	v_add_co_u32_e32 v2, vcc, 0xb000, v130
	s_nop 1
	v_addc_co_u32_e32 v3, vcc, 0, v131, vcc
	global_load_dwordx4 v[122:125], v[2:3], off nt
	global_load_dwordx4 v[34:37], v[2:3], off offset:2048 nt
	v_add_co_u32_e32 v2, vcc, 0xc000, v130
	s_nop 1
	v_addc_co_u32_e32 v3, vcc, 0, v131, vcc
	v_add_co_u32_e32 v6, vcc, 0xd000, v130
	global_load_dwordx4 v[10:13], v[2:3], off nt
	s_nop 0
	global_load_dwordx4 v[2:5], v[2:3], off offset:2048 nt
	v_addc_co_u32_e32 v7, vcc, 0, v131, vcc
	global_load_dwordx4 v[22:25], v[6:7], off nt
	global_load_dwordx4 v[14:17], v[6:7], off offset:2048 nt
	v_add_co_u32_e32 v6, vcc, 0xe000, v130
	s_nop 1
	v_addc_co_u32_e32 v7, vcc, 0, v131, vcc
	global_load_dwordx4 v[30:33], v[6:7], off nt
	global_load_dwordx4 v[18:21], v[6:7], off offset:2048 nt
	v_add_co_u32_e32 v6, vcc, 0xf000, v130
	s_nop 1
	v_addc_co_u32_e32 v7, vcc, 0, v131, vcc
	global_load_dwordx4 v[26:29], v[6:7], off nt
	s_nop 0
	global_load_dwordx4 v[6:9], v[6:7], off offset:2048 nt
	s_waitcnt lgkmcnt(0)
	s_barrier
	s_lshl_b32 s23, s47, 10
	s_cmp_gt_i32 s47, 1
	s_cbranch_scc1 .LBB0_622
	s_add_i32 s24, s23, 0
	v_lshl_add_u32 v135, v134, 2, s24
	ds_read_b128 v[136:139], v135
	v_cmp_eq_u32_e32 vcc, 0, v132
	s_waitcnt lgkmcnt(0)
	v_max_f32_e32 v130, v139, v139
	v_max_f32_e32 v131, v138, v138
	v_max_f32_e32 v130, v131, v130
	v_max3_f32 v130, v136, v137, v130
	s_nop 1
	v_mov_b32_dpp v131, v130 quad_perm:[1,0,3,2] row_mask:0xf bank_mask:0xf bound_ctrl:1
	v_max_f32_e32 v131, v131, v131
	v_max_f32_e32 v130, v130, v131
	s_nop 1
	v_mov_b32_dpp v131, v130 quad_perm:[2,3,0,1] row_mask:0xf bank_mask:0xf bound_ctrl:1
	v_max_f32_e32 v131, v131, v131
	v_max_f32_e32 v130, v130, v131
	s_nop 1
	v_mov_b32_dpp v131, v130 row_ror:4 row_mask:0xf bank_mask:0xf bound_ctrl:1
	v_max_f32_e32 v131, v131, v131
	v_max_f32_e32 v130, v130, v131
	s_nop 1
	v_mov_b32_dpp v131, v130 row_ror:8 row_mask:0xf bank_mask:0xf bound_ctrl:1
	v_max_f32_e32 v131, v131, v131
	v_max_f32_e32 v130, v130, v131
	v_mov_b32_e32 v131, v130
	s_nop 1
	v_permlane16_swap_b32_e32 v130, v131
	v_max_f32_e32 v131, v131, v131
	v_max_f32_e32 v130, v130, v130
	v_max_f32_e32 v130, v130, v131
	v_mov_b32_e32 v131, v130
	s_nop 1
	v_permlane32_swap_b32_e32 v130, v131
	v_max_f32_e32 v131, v131, v131
	v_max_f32_e32 v130, v130, v130
	v_max_f32_e32 v130, v130, v131
	v_sub_f32_e32 v131, v136, v130
	v_exp_f32_e32 v136, v131
	v_sub_f32_e32 v131, v137, v130
	v_exp_f32_e32 v137, v131
	v_sub_f32_e32 v131, v138, v130
	v_exp_f32_e32 v138, v131
	v_sub_f32_e32 v130, v139, v130
	v_exp_f32_e32 v139, v130
	v_add_f32_e32 v130, v136, v137
	v_add_f32_e32 v130, v138, v130
	v_add_f32_e32 v130, v139, v130
	ds_write_b128 v135, v[136:139]
	s_nop 0
	v_add_f32_dpp v130, v130, v130 quad_perm:[1,0,3,2] row_mask:0xf bank_mask:0xf bound_ctrl:1
	s_nop 1
	v_add_f32_dpp v130, v130, v130 quad_perm:[2,3,0,1] row_mask:0xf bank_mask:0xf bound_ctrl:1
	s_nop 1
	v_add_f32_dpp v130, v130, v130 row_ror:4 row_mask:0xf bank_mask:0xf bound_ctrl:1
	s_nop 1
	v_add_f32_dpp v130, v130, v130 row_ror:8 row_mask:0xf bank_mask:0xf bound_ctrl:1
	v_mov_b32_e32 v131, v130
	s_nop 1
	v_permlane16_swap_b32_e32 v130, v131
	v_add_f32_e32 v130, v130, v131
	v_mov_b32_e32 v131, v130
	s_nop 1
	v_permlane32_swap_b32_e32 v130, v131
	s_and_saveexec_b64 s[2:3], vcc
	s_cbranch_execz .LBB0_621
	v_add_f32_e32 v130, v130, v131
	v_div_scale_f32 v131, s[48:49], v130, v130, 1.0
	v_rcp_f32_e32 v132, v131
	v_div_scale_f32 v135, vcc, 1.0, v130, 1.0
	s_mulk_i32 s47, 0xfc04
	v_fma_f32 v136, -v131, v132, 1.0
	v_fmac_f32_e32 v132, v136, v132
	v_mul_f32_e32 v136, v135, v132
	v_fma_f32 v137, -v131, v136, v135
	v_fmac_f32_e32 v136, v137, v132
	v_fma_f32 v131, -v131, v136, v135
	v_div_fmas_f32 v131, v131, v132, v136
	s_add_i32 s24, s24, s47
	v_div_fixup_f32 v130, v131, v130, 1.0
	v_mov_b32_e32 v131, s24
	ds_write_b32 v131, v130 offset:2048

.LBB0_812:
	v_mov_b32_e32 v1, v0
	s_nop 0
	v_readfirstlane_b32 s2, v1
	s_ashr_i32 s43, s2, 6
	s_lshl_b32 s18, s43, 5
	s_ashr_i32 s19, s18, 31
	v_and_b32_e32 v132, 63, v1
	s_lshl_b64 s[2:3], s[18:19], 11
	v_lshl_or_b32 v106, v132, 4, s2
	s_add_u32 s2, s82, s6
	v_lshlrev_b32_e32 v2, 3, v132
	v_mov_b32_e32 v107, s3
	s_addc_u32 s3, s83, s7
	global_load_dwordx2 v[108:109], v2, s[14:15]
	v_lshl_add_u64 v[2:3], s[2:3], 0, v[106:107]
	v_add_co_u32_e32 v4, vcc, s22, v2
	global_load_dwordx4 v[138:141], v[2:3], off offset:1024 nt
	global_load_dwordx4 v[102:105], v[2:3], off offset:3072 nt
	v_addc_co_u32_e32 v5, vcc, 0, v3, vcc
	global_load_dwordx4 v[98:101], v[4:5], off offset:1024 nt
	global_load_dwordx4 v[94:97], v[4:5], off offset:3072 nt
	v_add_co_u32_e32 v4, vcc, s23, v2
	v_addc_co_u32_e32 v5, vcc, 0, v3, vcc
	global_load_dwordx4 v[90:93], v[4:5], off offset:1024 nt
	global_load_dwordx4 v[86:89], v[4:5], off offset:3072 nt
	v_add_co_u32_e32 v4, vcc, s24, v2
	s_nop 0
	v_addc_co_u32_e32 v5, vcc, 0, v3, vcc
	global_load_dwordx4 v[82:85], v[4:5], off offset:1024 nt
	global_load_dwordx4 v[78:81], v[4:5], off offset:3072 nt
	v_add_co_u32_e32 v4, vcc, s25, v2
	s_nop 0
	v_addc_co_u32_e32 v5, vcc, 0, v3, vcc
	global_load_dwordx4 v[74:77], v[4:5], off offset:1024 nt
	global_load_dwordx4 v[70:73], v[4:5], off offset:3072 nt
	v_add_co_u32_e32 v4, vcc, s28, v2
	s_nop 0
	v_addc_co_u32_e32 v5, vcc, 0, v3, vcc
	global_load_dwordx4 v[66:69], v[4:5], off offset:1024 nt
	global_load_dwordx4 v[62:65], v[4:5], off offset:3072 nt
	v_add_co_u32_e32 v4, vcc, s29, v2
	s_nop 1
	v_addc_co_u32_e32 v5, vcc, 0, v3, vcc
	global_load_dwordx4 v[58:61], v[4:5], off offset:1024 nt
	global_load_dwordx4 v[54:57], v[4:5], off offset:3072 nt
	v_add_co_u32_e32 v4, vcc, s30, v2
	s_nop 1
	v_addc_co_u32_e32 v5, vcc, 0, v3, vcc
	global_load_dwordx4 v[50:53], v[4:5], off offset:1024 nt
	global_load_dwordx4 v[46:49], v[4:5], off offset:3072 nt
	v_add_co_u32_e32 v4, vcc, s31, v2
	s_nop 1
	v_addc_co_u32_e32 v5, vcc, 0, v3, vcc
	global_load_dwordx4 v[126:129], v[4:5], off offset:1024 nt
	global_load_dwordx4 v[122:125], v[4:5], off offset:3072 nt
	v_add_co_u32_e32 v4, vcc, s33, v2
	s_nop 1
	v_addc_co_u32_e32 v5, vcc, 0, v3, vcc
	global_load_dwordx4 v[118:121], v[4:5], off offset:1024 nt
	global_load_dwordx4 v[114:117], v[4:5], off offset:3072 nt
	v_add_co_u32_e32 v4, vcc, s36, v2
	s_nop 1
	v_addc_co_u32_e32 v5, vcc, 0, v3, vcc
	global_load_dwordx4 v[110:113], v[4:5], off offset:1024 nt
	global_load_dwordx4 v[42:45], v[4:5], off offset:3072 nt
	v_add_co_u32_e32 v4, vcc, s37, v2
	s_nop 1
	v_addc_co_u32_e32 v5, vcc, 0, v3, vcc
	global_load_dwordx4 v[38:41], v[4:5], off offset:1024 nt
	global_load_dwordx4 v[34:37], v[4:5], off offset:3072 nt
	v_add_co_u32_e32 v4, vcc, s38, v2
	s_nop 1
	v_addc_co_u32_e32 v5, vcc, 0, v3, vcc
	global_load_dwordx4 v[30:33], v[4:5], off offset:1024 nt
	global_load_dwordx4 v[26:29], v[4:5], off offset:3072 nt
	v_add_co_u32_e32 v4, vcc, s39, v2
	s_nop 1
	v_addc_co_u32_e32 v5, vcc, 0, v3, vcc
	global_load_dwordx4 v[22:25], v[4:5], off offset:1024 nt
	global_load_dwordx4 v[18:21], v[4:5], off offset:3072 nt
	v_add_co_u32_e32 v4, vcc, s40, v2
	s_nop 1
	v_addc_co_u32_e32 v5, vcc, 0, v3, vcc
	v_add_co_u32_e32 v2, vcc, s41, v2
	global_load_dwordx4 v[14:17], v[4:5], off offset:1024 nt
	global_load_dwordx4 v[10:13], v[4:5], off offset:3072 nt
	v_addc_co_u32_e32 v3, vcc, 0, v3, vcc
	global_load_dwordx4 v[6:9], v[2:3], off offset:1024 nt
	s_nop 0
	global_load_dwordx4 v[2:5], v[2:3], off offset:3072 nt
	s_waitcnt vmcnt(32)
	v_lshlrev_b32_e32 v135, 16, v108
	v_and_b32_e32 v137, 0xffff0000, v108
	v_lshlrev_b32_e32 v136, 16, v109
	v_and_b32_e32 v134, 0xffff0000, v109
	v_and_b32_e32 v108, 31, v1
	v_cmp_eq_u32_e64 s[2:3], 0, v108
	v_lshlrev_b32_e32 v108, 5, v1
	v_and_b32_e32 v133, 0x400, v108
	s_waitcnt vmcnt(31)
	v_mul_f32_e32 v108, v139, v137
	v_fmac_f32_e32 v108, v138, v135
	v_fmac_f32_e32 v108, v140, v136
	v_fmac_f32_e32 v108, v141, v134
	s_lshl_b32 s19, s43, 7
	s_add_i32 s19, s19, 0
	v_add_f32_dpp v108, v108, v108 quad_perm:[1,0,3,2] row_mask:0xf bank_mask:0xf bound_ctrl:1
	v_add_u32_e32 v138, s19, v133
	s_nop 0
	v_add_f32_dpp v108, v108, v108 quad_perm:[2,3,0,1] row_mask:0xf bank_mask:0xf bound_ctrl:1
	s_nop 1
	v_add_f32_dpp v108, v108, v108 row_ror:4 row_mask:0xf bank_mask:0xf bound_ctrl:1
	s_nop 1
	v_add_f32_dpp v108, v108, v108 row_ror:8 row_mask:0xf bank_mask:0xf bound_ctrl:1
	v_mov_b32_e32 v109, v108
	s_nop 1
	v_permlane16_swap_b32_e32 v108, v109
	s_and_saveexec_b64 s[20:21], s[2:3]
	v_add_f32_e32 v108, v108, v109
	ds_write_b32 v138, v108
	s_or_b64 exec, exec, s[20:21]
	s_waitcnt vmcnt(30)
	v_mul_f32_e32 v103, v103, v137
	v_fmac_f32_e32 v103, v102, v135
	v_fmac_f32_e32 v103, v104, v136
	v_fmac_f32_e32 v103, v105, v134
	s_nop 1
	v_add_f32_dpp v102, v103, v103 quad_perm:[1,0,3,2] row_mask:0xf bank_mask:0xf bound_ctrl:1
	s_nop 1
	v_add_f32_dpp v102, v102, v102 quad_perm:[2,3,0,1] row_mask:0xf bank_mask:0xf bound_ctrl:1
	s_nop 1
	v_add_f32_dpp v102, v102, v102 row_ror:4 row_mask:0xf bank_mask:0xf bound_ctrl:1
	s_nop 1
	v_add_f32_dpp v102, v102, v102 row_ror:8 row_mask:0xf bank_mask:0xf bound_ctrl:1
	v_mov_b32_e32 v103, v102
	s_nop 1
	v_permlane16_swap_b32_e32 v102, v103
	s_and_saveexec_b64 s[20:21], s[2:3]
	v_add_f32_e32 v102, v102, v103
	ds_write_b32 v138, v102 offset:4
	s_or_b64 exec, exec, s[20:21]
	s_waitcnt vmcnt(29)
	v_mul_f32_e32 v99, v99, v137
	v_fmac_f32_e32 v99, v98, v135
	v_fmac_f32_e32 v99, v100, v136
	v_fmac_f32_e32 v99, v101, v134
	s_nop 1
	v_add_f32_dpp v98, v99, v99 quad_perm:[1,0,3,2] row_mask:0xf bank_mask:0xf bound_ctrl:1
	s_nop 1
	v_add_f32_dpp v98, v98, v98 quad_perm:[2,3,0,1] row_mask:0xf bank_mask:0xf bound_ctrl:1
	s_nop 1
	v_add_f32_dpp v98, v98, v98 row_ror:4 row_mask:0xf bank_mask:0xf bound_ctrl:1
	s_nop 1
	v_add_f32_dpp v98, v98, v98 row_ror:8 row_mask:0xf bank_mask:0xf bound_ctrl:1
	v_mov_b32_e32 v99, v98
	s_nop 1
	v_permlane16_swap_b32_e32 v98, v99
	s_and_saveexec_b64 s[20:21], s[2:3]
	v_add_f32_e32 v98, v98, v99
	ds_write_b32 v138, v98 offset:8
	s_or_b64 exec, exec, s[20:21]
	s_waitcnt vmcnt(28)
	v_mul_f32_e32 v95, v95, v137
	v_fmac_f32_e32 v95, v94, v135
	v_fmac_f32_e32 v95, v96, v136
	v_fmac_f32_e32 v95, v97, v134
	s_nop 1
	v_add_f32_dpp v94, v95, v95 quad_perm:[1,0,3,2] row_mask:0xf bank_mask:0xf bound_ctrl:1
	s_nop 1
	v_add_f32_dpp v94, v94, v94 quad_perm:[2,3,0,1] row_mask:0xf bank_mask:0xf bound_ctrl:1
	s_nop 1
	v_add_f32_dpp v94, v94, v94 row_ror:4 row_mask:0xf bank_mask:0xf bound_ctrl:1
	s_nop 1
	v_add_f32_dpp v94, v94, v94 row_ror:8 row_mask:0xf bank_mask:0xf bound_ctrl:1
	v_mov_b32_e32 v95, v94
	s_nop 1
	v_permlane16_swap_b32_e32 v94, v95
	s_and_saveexec_b64 s[20:21], s[2:3]
	v_add_f32_e32 v94, v94, v95
	ds_write_b32 v138, v94 offset:12
	s_or_b64 exec, exec, s[20:21]
	s_waitcnt vmcnt(27)
	v_mul_f32_e32 v91, v91, v137
	v_fmac_f32_e32 v91, v90, v135
	v_fmac_f32_e32 v91, v92, v136
	v_fmac_f32_e32 v91, v93, v134
	s_nop 1
	v_add_f32_dpp v90, v91, v91 quad_perm:[1,0,3,2] row_mask:0xf bank_mask:0xf bound_ctrl:1
	s_nop 1
	v_add_f32_dpp v90, v90, v90 quad_perm:[2,3,0,1] row_mask:0xf bank_mask:0xf bound_ctrl:1
	s_nop 1
	v_add_f32_dpp v90, v90, v90 row_ror:4 row_mask:0xf bank_mask:0xf bound_ctrl:1
	s_nop 1
	v_add_f32_dpp v90, v90, v90 row_ror:8 row_mask:0xf bank_mask:0xf bound_ctrl:1
	v_mov_b32_e32 v91, v90
	s_nop 1
	v_permlane16_swap_b32_e32 v90, v91
	s_and_saveexec_b64 s[20:21], s[2:3]
	v_add_f32_e32 v90, v90, v91
	ds_write_b32 v138, v90 offset:16
	s_or_b64 exec, exec, s[20:21]
	s_waitcnt vmcnt(26)
	v_mul_f32_e32 v87, v87, v137
	v_fmac_f32_e32 v87, v86, v135
	v_fmac_f32_e32 v87, v88, v136
	v_fmac_f32_e32 v87, v89, v134
	s_nop 1
	v_add_f32_dpp v86, v87, v87 quad_perm:[1,0,3,2] row_mask:0xf bank_mask:0xf bound_ctrl:1
	s_nop 1
	v_add_f32_dpp v86, v86, v86 quad_perm:[2,3,0,1] row_mask:0xf bank_mask:0xf bound_ctrl:1
	s_nop 1
	v_add_f32_dpp v86, v86, v86 row_ror:4 row_mask:0xf bank_mask:0xf bound_ctrl:1
	s_nop 1
	v_add_f32_dpp v86, v86, v86 row_ror:8 row_mask:0xf bank_mask:0xf bound_ctrl:1
	v_mov_b32_e32 v87, v86
	s_nop 1
	v_permlane16_swap_b32_e32 v86, v87
	s_and_saveexec_b64 s[20:21], s[2:3]
	v_add_f32_e32 v86, v86, v87
	ds_write_b32 v138, v86 offset:20
	s_or_b64 exec, exec, s[20:21]
	s_waitcnt vmcnt(25)
	v_mul_f32_e32 v83, v83, v137
	v_fmac_f32_e32 v83, v82, v135
	v_fmac_f32_e32 v83, v84, v136
	v_fmac_f32_e32 v83, v85, v134
	s_nop 1
	v_add_f32_dpp v82, v83, v83 quad_perm:[1,0,3,2] row_mask:0xf bank_mask:0xf bound_ctrl:1
	s_nop 1
	v_add_f32_dpp v82, v82, v82 quad_perm:[2,3,0,1] row_mask:0xf bank_mask:0xf bound_ctrl:1
	s_nop 1
	v_add_f32_dpp v82, v82, v82 row_ror:4 row_mask:0xf bank_mask:0xf bound_ctrl:1
	s_nop 1
	v_add_f32_dpp v82, v82, v82 row_ror:8 row_mask:0xf bank_mask:0xf bound_ctrl:1
	v_mov_b32_e32 v83, v82
	s_nop 1
	v_permlane16_swap_b32_e32 v82, v83
	s_and_saveexec_b64 s[20:21], s[2:3]
	v_add_f32_e32 v82, v82, v83
	ds_write_b32 v138, v82 offset:24
	s_or_b64 exec, exec, s[20:21]
	s_waitcnt vmcnt(24)
	v_mul_f32_e32 v79, v79, v137
	v_fmac_f32_e32 v79, v78, v135
	v_fmac_f32_e32 v79, v80, v136
	v_fmac_f32_e32 v79, v81, v134
	s_nop 1
	v_add_f32_dpp v78, v79, v79 quad_perm:[1,0,3,2] row_mask:0xf bank_mask:0xf bound_ctrl:1
	s_nop 1
	v_add_f32_dpp v78, v78, v78 quad_perm:[2,3,0,1] row_mask:0xf bank_mask:0xf bound_ctrl:1
	s_nop 1
	v_add_f32_dpp v78, v78, v78 row_ror:4 row_mask:0xf bank_mask:0xf bound_ctrl:1
	s_nop 1
	v_add_f32_dpp v78, v78, v78 row_ror:8 row_mask:0xf bank_mask:0xf bound_ctrl:1
	v_mov_b32_e32 v79, v78
	s_nop 1
	v_permlane16_swap_b32_e32 v78, v79
	s_and_saveexec_b64 s[20:21], s[2:3]
	v_add_f32_e32 v78, v78, v79
	ds_write_b32 v138, v78 offset:28
	s_or_b64 exec, exec, s[20:21]
	s_waitcnt vmcnt(23)
	v_mul_f32_e32 v75, v75, v137
	v_fmac_f32_e32 v75, v74, v135
	v_fmac_f32_e32 v75, v76, v136
	v_fmac_f32_e32 v75, v77, v134
	s_nop 1
	v_add_f32_dpp v74, v75, v75 quad_perm:[1,0,3,2] row_mask:0xf bank_mask:0xf bound_ctrl:1
	s_nop 1
	v_add_f32_dpp v74, v74, v74 quad_perm:[2,3,0,1] row_mask:0xf bank_mask:0xf bound_ctrl:1
	s_nop 1
	v_add_f32_dpp v74, v74, v74 row_ror:4 row_mask:0xf bank_mask:0xf bound_ctrl:1
	s_nop 1
	v_add_f32_dpp v74, v74, v74 row_ror:8 row_mask:0xf bank_mask:0xf bound_ctrl:1
	v_mov_b32_e32 v75, v74
	s_nop 1
	v_permlane16_swap_b32_e32 v74, v75
	s_and_saveexec_b64 s[20:21], s[2:3]
	v_add_f32_e32 v74, v74, v75
	ds_write_b32 v138, v74 offset:32
	s_or_b64 exec, exec, s[20:21]
	s_waitcnt vmcnt(22)
	v_mul_f32_e32 v71, v71, v137
	v_fmac_f32_e32 v71, v70, v135
	v_fmac_f32_e32 v71, v72, v136
	v_fmac_f32_e32 v71, v73, v134
	s_nop 1
	v_add_f32_dpp v70, v71, v71 quad_perm:[1,0,3,2] row_mask:0xf bank_mask:0xf bound_ctrl:1
	s_nop 1
	v_add_f32_dpp v70, v70, v70 quad_perm:[2,3,0,1] row_mask:0xf bank_mask:0xf bound_ctrl:1
	s_nop 1
	v_add_f32_dpp v70, v70, v70 row_ror:4 row_mask:0xf bank_mask:0xf bound_ctrl:1
	s_nop 1
	v_add_f32_dpp v70, v70, v70 row_ror:8 row_mask:0xf bank_mask:0xf bound_ctrl:1
	v_mov_b32_e32 v71, v70
	s_nop 1
	v_permlane16_swap_b32_e32 v70, v71
	s_and_saveexec_b64 s[20:21], s[2:3]
	v_add_f32_e32 v70, v70, v71
	ds_write_b32 v138, v70 offset:36
	s_or_b64 exec, exec, s[20:21]
	s_waitcnt vmcnt(21)
	v_mul_f32_e32 v67, v67, v137
	v_fmac_f32_e32 v67, v66, v135
	v_fmac_f32_e32 v67, v68, v136
	v_fmac_f32_e32 v67, v69, v134
	s_nop 1
	v_add_f32_dpp v66, v67, v67 quad_perm:[1,0,3,2] row_mask:0xf bank_mask:0xf bound_ctrl:1
	s_nop 1
	v_add_f32_dpp v66, v66, v66 quad_perm:[2,3,0,1] row_mask:0xf bank_mask:0xf bound_ctrl:1
	s_nop 1
	v_add_f32_dpp v66, v66, v66 row_ror:4 row_mask:0xf bank_mask:0xf bound_ctrl:1
	s_nop 1
	v_add_f32_dpp v66, v66, v66 row_ror:8 row_mask:0xf bank_mask:0xf bound_ctrl:1
	v_mov_b32_e32 v67, v66
	s_nop 1
	v_permlane16_swap_b32_e32 v66, v67
	s_and_saveexec_b64 s[20:21], s[2:3]
	v_add_f32_e32 v66, v66, v67
	ds_write_b32 v138, v66 offset:40
	s_or_b64 exec, exec, s[20:21]
	s_waitcnt vmcnt(20)
	v_mul_f32_e32 v63, v63, v137
	v_fmac_f32_e32 v63, v62, v135
	v_fmac_f32_e32 v63, v64, v136
	v_fmac_f32_e32 v63, v65, v134
	s_nop 1
	v_add_f32_dpp v62, v63, v63 quad_perm:[1,0,3,2] row_mask:0xf bank_mask:0xf bound_ctrl:1
	s_nop 1
	v_add_f32_dpp v62, v62, v62 quad_perm:[2,3,0,1] row_mask:0xf bank_mask:0xf bound_ctrl:1
	s_nop 1
	v_add_f32_dpp v62, v62, v62 row_ror:4 row_mask:0xf bank_mask:0xf bound_ctrl:1
	s_nop 1
	v_add_f32_dpp v62, v62, v62 row_ror:8 row_mask:0xf bank_mask:0xf bound_ctrl:1
	v_mov_b32_e32 v63, v62
	s_nop 1
	v_permlane16_swap_b32_e32 v62, v63
	s_and_saveexec_b64 s[20:21], s[2:3]
	v_add_f32_e32 v62, v62, v63
	ds_write_b32 v138, v62 offset:44
	s_or_b64 exec, exec, s[20:21]
	s_waitcnt vmcnt(19)
	v_mul_f32_e32 v59, v59, v137
	v_fmac_f32_e32 v59, v58, v135
	v_fmac_f32_e32 v59, v60, v136
	v_fmac_f32_e32 v59, v61, v134
	s_nop 1
	v_add_f32_dpp v58, v59, v59 quad_perm:[1,0,3,2] row_mask:0xf bank_mask:0xf bound_ctrl:1
	s_nop 1
	v_add_f32_dpp v58, v58, v58 quad_perm:[2,3,0,1] row_mask:0xf bank_mask:0xf bound_ctrl:1
	s_nop 1
	v_add_f32_dpp v58, v58, v58 row_ror:4 row_mask:0xf bank_mask:0xf bound_ctrl:1
	s_nop 1
	v_add_f32_dpp v58, v58, v58 row_ror:8 row_mask:0xf bank_mask:0xf bound_ctrl:1
	v_mov_b32_e32 v59, v58
	s_nop 1
	v_permlane16_swap_b32_e32 v58, v59
	s_and_saveexec_b64 s[20:21], s[2:3]
	v_add_f32_e32 v58, v58, v59
	ds_write_b32 v138, v58 offset:48
	s_or_b64 exec, exec, s[20:21]
	s_waitcnt vmcnt(18)
	v_mul_f32_e32 v55, v55, v137
	v_fmac_f32_e32 v55, v54, v135
	v_fmac_f32_e32 v55, v56, v136
	v_fmac_f32_e32 v55, v57, v134
	s_nop 1
	v_add_f32_dpp v54, v55, v55 quad_perm:[1,0,3,2] row_mask:0xf bank_mask:0xf bound_ctrl:1
	s_nop 1
	v_add_f32_dpp v54, v54, v54 quad_perm:[2,3,0,1] row_mask:0xf bank_mask:0xf bound_ctrl:1
	s_nop 1
	v_add_f32_dpp v54, v54, v54 row_ror:4 row_mask:0xf bank_mask:0xf bound_ctrl:1
	s_nop 1
	v_add_f32_dpp v54, v54, v54 row_ror:8 row_mask:0xf bank_mask:0xf bound_ctrl:1
	v_mov_b32_e32 v55, v54
	s_nop 1
	v_permlane16_swap_b32_e32 v54, v55
	s_and_saveexec_b64 s[20:21], s[2:3]
	v_add_f32_e32 v54, v54, v55
	ds_write_b32 v138, v54 offset:52
	s_or_b64 exec, exec, s[20:21]
	s_waitcnt vmcnt(17)
	v_mul_f32_e32 v51, v51, v137
	v_fmac_f32_e32 v51, v50, v135
	v_fmac_f32_e32 v51, v52, v136
	v_fmac_f32_e32 v51, v53, v134
	s_nop 1
	v_add_f32_dpp v50, v51, v51 quad_perm:[1,0,3,2] row_mask:0xf bank_mask:0xf bound_ctrl:1
	s_nop 1
	v_add_f32_dpp v50, v50, v50 quad_perm:[2,3,0,1] row_mask:0xf bank_mask:0xf bound_ctrl:1
	s_nop 1
	v_add_f32_dpp v50, v50, v50 row_ror:4 row_mask:0xf bank_mask:0xf bound_ctrl:1
	s_nop 1
	v_add_f32_dpp v50, v50, v50 row_ror:8 row_mask:0xf bank_mask:0xf bound_ctrl:1
	v_mov_b32_e32 v51, v50
	s_nop 1
	v_permlane16_swap_b32_e32 v50, v51
	s_and_saveexec_b64 s[20:21], s[2:3]
	v_add_f32_e32 v50, v50, v51
	ds_write_b32 v138, v50 offset:56
	s_or_b64 exec, exec, s[20:21]
	s_waitcnt vmcnt(16)
	v_mul_f32_e32 v47, v47, v137
	v_fmac_f32_e32 v47, v46, v135
	v_fmac_f32_e32 v47, v48, v136
	v_fmac_f32_e32 v47, v49, v134
	s_nop 1
	v_add_f32_dpp v46, v47, v47 quad_perm:[1,0,3,2] row_mask:0xf bank_mask:0xf bound_ctrl:1
	s_nop 1
	v_add_f32_dpp v46, v46, v46 quad_perm:[2,3,0,1] row_mask:0xf bank_mask:0xf bound_ctrl:1
	s_nop 1
	v_add_f32_dpp v46, v46, v46 row_ror:4 row_mask:0xf bank_mask:0xf bound_ctrl:1
	s_nop 1
	v_add_f32_dpp v46, v46, v46 row_ror:8 row_mask:0xf bank_mask:0xf bound_ctrl:1
	v_mov_b32_e32 v47, v46
	s_nop 1
	v_permlane16_swap_b32_e32 v46, v47
	s_and_saveexec_b64 s[20:21], s[2:3]
	v_add_f32_e32 v46, v46, v47
	ds_write_b32 v138, v46 offset:60
	s_or_b64 exec, exec, s[20:21]
	v_readlane_b32 s44, v245, 9
	v_readlane_b32 s45, v245, 10
	s_add_u32 s20, s44, s6
	s_addc_u32 s21, s45, s7
	v_lshl_add_u64 v[130:131], s[20:21], 0, v[106:107]
	v_readlane_b32 s46, v245, 11
	v_readlane_b32 s47, v245, 12
	v_readlane_b32 s48, v245, 13
	v_readlane_b32 s49, v245, 14
	v_readlane_b32 s50, v245, 15
	v_readlane_b32 s51, v245, 16
	v_readlane_b32 s52, v245, 17
	v_readlane_b32 s53, v245, 18
	v_readlane_b32 s54, v245, 19
	v_readlane_b32 s55, v245, 20
	v_readlane_b32 s56, v245, 21
	v_readlane_b32 s57, v245, 22
	v_readlane_b32 s58, v245, 23
	v_readlane_b32 s59, v245, 24
	v_add_co_u32_e32 v46, vcc, 0x1000, v130
	global_load_dwordx4 v[106:109], v[130:131], off offset:1024 nt
	global_load_dwordx4 v[94:97], v[130:131], off offset:3072 nt
	v_addc_co_u32_e32 v47, vcc, 0, v131, vcc
	global_load_dwordx4 v[102:105], v[46:47], off offset:1024 nt
	global_load_dwordx4 v[78:81], v[46:47], off offset:3072 nt
	v_add_co_u32_e32 v46, vcc, 0x2000, v130
	s_nop 1
	v_addc_co_u32_e32 v47, vcc, 0, v131, vcc
	global_load_dwordx4 v[98:101], v[46:47], off offset:1024 nt
	global_load_dwordx4 v[82:85], v[46:47], off offset:3072 nt
	v_add_co_u32_e32 v46, vcc, 0x3000, v130
	s_nop 1
	v_addc_co_u32_e32 v47, vcc, 0, v131, vcc
	global_load_dwordx4 v[90:93], v[46:47], off offset:1024 nt
	global_load_dwordx4 v[62:65], v[46:47], off offset:3072 nt
	v_add_co_u32_e32 v46, vcc, 0x4000, v130
	s_nop 1
	v_addc_co_u32_e32 v47, vcc, 0, v131, vcc
	global_load_dwordx4 v[86:89], v[46:47], off offset:1024 nt
	global_load_dwordx4 v[66:69], v[46:47], off offset:3072 nt
	v_add_co_u32_e32 v46, vcc, 0x5000, v130
	s_nop 1
	v_addc_co_u32_e32 v47, vcc, 0, v131, vcc
	global_load_dwordx4 v[74:77], v[46:47], off offset:1024 nt
	global_load_dwordx4 v[50:53], v[46:47], off offset:3072 nt
	v_add_co_u32_e32 v46, vcc, 0x6000, v130
	s_nop 1
	v_addc_co_u32_e32 v47, vcc, 0, v131, vcc
	global_load_dwordx4 v[70:73], v[46:47], off offset:1024 nt
	global_load_dwordx4 v[54:57], v[46:47], off offset:3072 nt
	v_add_co_u32_e32 v46, vcc, 0x7000, v130
	s_nop 1
	v_addc_co_u32_e32 v47, vcc, 0, v131, vcc
	global_load_dwordx4 v[58:61], v[46:47], off offset:1024 nt
	s_nop 0
	global_load_dwordx4 v[46:49], v[46:47], off offset:3072 nt
	s_waitcnt vmcnt(31)
	v_mul_f32_e32 v127, v127, v137
	v_fmac_f32_e32 v127, v126, v135
	v_fmac_f32_e32 v127, v128, v136
	v_fmac_f32_e32 v127, v129, v134
	s_nop 1
	v_add_f32_dpp v126, v127, v127 quad_perm:[1,0,3,2] row_mask:0xf bank_mask:0xf bound_ctrl:1
	s_nop 1
	v_add_f32_dpp v126, v126, v126 quad_perm:[2,3,0,1] row_mask:0xf bank_mask:0xf bound_ctrl:1
	s_nop 1
	v_add_f32_dpp v126, v126, v126 row_ror:4 row_mask:0xf bank_mask:0xf bound_ctrl:1
	s_nop 1
	v_add_f32_dpp v126, v126, v126 row_ror:8 row_mask:0xf bank_mask:0xf bound_ctrl:1
	v_mov_b32_e32 v127, v126
	s_nop 1
	v_permlane16_swap_b32_e32 v126, v127
	s_and_saveexec_b64 s[20:21], s[2:3]
	v_add_f32_e32 v126, v126, v127
	ds_write_b32 v138, v126 offset:64
	s_or_b64 exec, exec, s[20:21]
	s_waitcnt vmcnt(30)
	v_mul_f32_e32 v123, v123, v137
	v_fmac_f32_e32 v123, v122, v135
	v_fmac_f32_e32 v123, v124, v136
	v_fmac_f32_e32 v123, v125, v134
	s_nop 1
	v_add_f32_dpp v122, v123, v123 quad_perm:[1,0,3,2] row_mask:0xf bank_mask:0xf bound_ctrl:1
	s_nop 1
	v_add_f32_dpp v122, v122, v122 quad_perm:[2,3,0,1] row_mask:0xf bank_mask:0xf bound_ctrl:1
	s_nop 1
	v_add_f32_dpp v122, v122, v122 row_ror:4 row_mask:0xf bank_mask:0xf bound_ctrl:1
	s_nop 1
	v_add_f32_dpp v122, v122, v122 row_ror:8 row_mask:0xf bank_mask:0xf bound_ctrl:1
	v_mov_b32_e32 v123, v122
	s_nop 1
	v_permlane16_swap_b32_e32 v122, v123
	s_and_saveexec_b64 s[20:21], s[2:3]
	v_add_f32_e32 v122, v122, v123
	ds_write_b32 v138, v122 offset:68
	s_or_b64 exec, exec, s[20:21]
	s_waitcnt vmcnt(29)
	v_mul_f32_e32 v119, v119, v137
	v_fmac_f32_e32 v119, v118, v135
	v_fmac_f32_e32 v119, v120, v136
	v_fmac_f32_e32 v119, v121, v134
	s_nop 1
	v_add_f32_dpp v118, v119, v119 quad_perm:[1,0,3,2] row_mask:0xf bank_mask:0xf bound_ctrl:1
	s_nop 1
	v_add_f32_dpp v118, v118, v118 quad_perm:[2,3,0,1] row_mask:0xf bank_mask:0xf bound_ctrl:1
	s_nop 1
	v_add_f32_dpp v118, v118, v118 row_ror:4 row_mask:0xf bank_mask:0xf bound_ctrl:1
	s_nop 1
	v_add_f32_dpp v118, v118, v118 row_ror:8 row_mask:0xf bank_mask:0xf bound_ctrl:1
	v_mov_b32_e32 v119, v118
	s_nop 1
	v_permlane16_swap_b32_e32 v118, v119
	s_and_saveexec_b64 s[20:21], s[2:3]
	v_add_f32_e32 v118, v118, v119
	ds_write_b32 v138, v118 offset:72
	s_or_b64 exec, exec, s[20:21]
	s_waitcnt vmcnt(28)
	v_mul_f32_e32 v115, v115, v137
	v_fmac_f32_e32 v115, v114, v135
	v_fmac_f32_e32 v115, v116, v136
	v_fmac_f32_e32 v115, v117, v134
	s_nop 1
	v_add_f32_dpp v114, v115, v115 quad_perm:[1,0,3,2] row_mask:0xf bank_mask:0xf bound_ctrl:1
	s_nop 1
	v_add_f32_dpp v114, v114, v114 quad_perm:[2,3,0,1] row_mask:0xf bank_mask:0xf bound_ctrl:1
	s_nop 1
	v_add_f32_dpp v114, v114, v114 row_ror:4 row_mask:0xf bank_mask:0xf bound_ctrl:1
	s_nop 1
	v_add_f32_dpp v114, v114, v114 row_ror:8 row_mask:0xf bank_mask:0xf bound_ctrl:1
	v_mov_b32_e32 v115, v114
	s_nop 1
	v_permlane16_swap_b32_e32 v114, v115
	s_and_saveexec_b64 s[20:21], s[2:3]
	v_add_f32_e32 v114, v114, v115
	ds_write_b32 v138, v114 offset:76
	s_or_b64 exec, exec, s[20:21]
	s_waitcnt vmcnt(27)
	v_mul_f32_e32 v111, v111, v137
	v_fmac_f32_e32 v111, v110, v135
	v_fmac_f32_e32 v111, v112, v136
	v_fmac_f32_e32 v111, v113, v134
	s_nop 1
	v_add_f32_dpp v110, v111, v111 quad_perm:[1,0,3,2] row_mask:0xf bank_mask:0xf bound_ctrl:1
	s_nop 1
	v_add_f32_dpp v110, v110, v110 quad_perm:[2,3,0,1] row_mask:0xf bank_mask:0xf bound_ctrl:1
	s_nop 1
	v_add_f32_dpp v110, v110, v110 row_ror:4 row_mask:0xf bank_mask:0xf bound_ctrl:1
	s_nop 1
	v_add_f32_dpp v110, v110, v110 row_ror:8 row_mask:0xf bank_mask:0xf bound_ctrl:1
	v_mov_b32_e32 v111, v110
	s_nop 1
	v_permlane16_swap_b32_e32 v110, v111
	s_and_saveexec_b64 s[20:21], s[2:3]
	v_add_f32_e32 v110, v110, v111
	ds_write_b32 v138, v110 offset:80
	s_or_b64 exec, exec, s[20:21]
	s_waitcnt vmcnt(26)
	v_mul_f32_e32 v43, v43, v137
	v_fmac_f32_e32 v43, v42, v135
	v_fmac_f32_e32 v43, v44, v136
	v_fmac_f32_e32 v43, v45, v134
	s_nop 1
	v_add_f32_dpp v42, v43, v43 quad_perm:[1,0,3,2] row_mask:0xf bank_mask:0xf bound_ctrl:1
	s_nop 1
	v_add_f32_dpp v42, v42, v42 quad_perm:[2,3,0,1] row_mask:0xf bank_mask:0xf bound_ctrl:1
	s_nop 1
	v_add_f32_dpp v42, v42, v42 row_ror:4 row_mask:0xf bank_mask:0xf bound_ctrl:1
	s_nop 1
	v_add_f32_dpp v42, v42, v42 row_ror:8 row_mask:0xf bank_mask:0xf bound_ctrl:1
	v_mov_b32_e32 v43, v42
	s_nop 1
	v_permlane16_swap_b32_e32 v42, v43
	s_and_saveexec_b64 s[20:21], s[2:3]
	v_add_f32_e32 v42, v42, v43
	ds_write_b32 v138, v42 offset:84
	s_or_b64 exec, exec, s[20:21]
	s_waitcnt vmcnt(25)
	v_mul_f32_e32 v39, v39, v137
	v_fmac_f32_e32 v39, v38, v135
	v_fmac_f32_e32 v39, v40, v136
	v_fmac_f32_e32 v39, v41, v134
	s_nop 1
	v_add_f32_dpp v38, v39, v39 quad_perm:[1,0,3,2] row_mask:0xf bank_mask:0xf bound_ctrl:1
	s_nop 1
	v_add_f32_dpp v38, v38, v38 quad_perm:[2,3,0,1] row_mask:0xf bank_mask:0xf bound_ctrl:1
	s_nop 1
	v_add_f32_dpp v38, v38, v38 row_ror:4 row_mask:0xf bank_mask:0xf bound_ctrl:1
	s_nop 1
	v_add_f32_dpp v38, v38, v38 row_ror:8 row_mask:0xf bank_mask:0xf bound_ctrl:1
	v_mov_b32_e32 v39, v38
	s_nop 1
	v_permlane16_swap_b32_e32 v38, v39
	s_and_saveexec_b64 s[20:21], s[2:3]
	v_add_f32_e32 v38, v38, v39
	ds_write_b32 v138, v38 offset:88
	s_or_b64 exec, exec, s[20:21]
	s_waitcnt vmcnt(24)
	v_mul_f32_e32 v35, v35, v137
	v_fmac_f32_e32 v35, v34, v135
	v_fmac_f32_e32 v35, v36, v136
	v_fmac_f32_e32 v35, v37, v134
	s_nop 1
	v_add_f32_dpp v34, v35, v35 quad_perm:[1,0,3,2] row_mask:0xf bank_mask:0xf bound_ctrl:1
	s_nop 1
	v_add_f32_dpp v34, v34, v34 quad_perm:[2,3,0,1] row_mask:0xf bank_mask:0xf bound_ctrl:1
	s_nop 1
	v_add_f32_dpp v34, v34, v34 row_ror:4 row_mask:0xf bank_mask:0xf bound_ctrl:1
	s_nop 1
	v_add_f32_dpp v34, v34, v34 row_ror:8 row_mask:0xf bank_mask:0xf bound_ctrl:1
	v_mov_b32_e32 v35, v34
	s_nop 1
	v_permlane16_swap_b32_e32 v34, v35
	s_and_saveexec_b64 s[20:21], s[2:3]
	v_add_f32_e32 v34, v34, v35
	ds_write_b32 v138, v34 offset:92
	s_or_b64 exec, exec, s[20:21]
	s_waitcnt vmcnt(23)
	v_mul_f32_e32 v31, v31, v137
	v_fmac_f32_e32 v31, v30, v135
	v_fmac_f32_e32 v31, v32, v136
	v_fmac_f32_e32 v31, v33, v134
	s_nop 1
	v_add_f32_dpp v30, v31, v31 quad_perm:[1,0,3,2] row_mask:0xf bank_mask:0xf bound_ctrl:1
	s_nop 1
	v_add_f32_dpp v30, v30, v30 quad_perm:[2,3,0,1] row_mask:0xf bank_mask:0xf bound_ctrl:1
	s_nop 1
	v_add_f32_dpp v30, v30, v30 row_ror:4 row_mask:0xf bank_mask:0xf bound_ctrl:1
	s_nop 1
	v_add_f32_dpp v30, v30, v30 row_ror:8 row_mask:0xf bank_mask:0xf bound_ctrl:1
	v_mov_b32_e32 v31, v30
	s_nop 1
	v_permlane16_swap_b32_e32 v30, v31
	s_and_saveexec_b64 s[20:21], s[2:3]
	v_add_f32_e32 v30, v30, v31
	ds_write_b32 v138, v30 offset:96
	s_or_b64 exec, exec, s[20:21]
	s_waitcnt vmcnt(22)
	v_mul_f32_e32 v27, v27, v137
	v_fmac_f32_e32 v27, v26, v135
	v_fmac_f32_e32 v27, v28, v136
	v_fmac_f32_e32 v27, v29, v134
	s_nop 1
	v_add_f32_dpp v26, v27, v27 quad_perm:[1,0,3,2] row_mask:0xf bank_mask:0xf bound_ctrl:1
	s_nop 1
	v_add_f32_dpp v26, v26, v26 quad_perm:[2,3,0,1] row_mask:0xf bank_mask:0xf bound_ctrl:1
	s_nop 1
	v_add_f32_dpp v26, v26, v26 row_ror:4 row_mask:0xf bank_mask:0xf bound_ctrl:1
	s_nop 1
	v_add_f32_dpp v26, v26, v26 row_ror:8 row_mask:0xf bank_mask:0xf bound_ctrl:1
	v_mov_b32_e32 v27, v26
	s_nop 1
	v_permlane16_swap_b32_e32 v26, v27
	s_and_saveexec_b64 s[20:21], s[2:3]
	v_add_f32_e32 v26, v26, v27
	ds_write_b32 v138, v26 offset:100
	s_or_b64 exec, exec, s[20:21]
	s_waitcnt vmcnt(21)
	v_mul_f32_e32 v23, v23, v137
	v_fmac_f32_e32 v23, v22, v135
	v_fmac_f32_e32 v23, v24, v136
	v_fmac_f32_e32 v23, v25, v134
	s_nop 1
	v_add_f32_dpp v22, v23, v23 quad_perm:[1,0,3,2] row_mask:0xf bank_mask:0xf bound_ctrl:1
	s_nop 1
	v_add_f32_dpp v22, v22, v22 quad_perm:[2,3,0,1] row_mask:0xf bank_mask:0xf bound_ctrl:1
	s_nop 1
	v_add_f32_dpp v22, v22, v22 row_ror:4 row_mask:0xf bank_mask:0xf bound_ctrl:1
	s_nop 1
	v_add_f32_dpp v22, v22, v22 row_ror:8 row_mask:0xf bank_mask:0xf bound_ctrl:1
	v_mov_b32_e32 v23, v22
	s_nop 1
	v_permlane16_swap_b32_e32 v22, v23
	s_and_saveexec_b64 s[20:21], s[2:3]
	v_add_f32_e32 v22, v22, v23
	ds_write_b32 v138, v22 offset:104
	s_or_b64 exec, exec, s[20:21]
	s_waitcnt vmcnt(20)
	v_mul_f32_e32 v19, v19, v137
	v_fmac_f32_e32 v19, v18, v135
	v_fmac_f32_e32 v19, v20, v136
	v_fmac_f32_e32 v19, v21, v134
	s_nop 1
	v_add_f32_dpp v18, v19, v19 quad_perm:[1,0,3,2] row_mask:0xf bank_mask:0xf bound_ctrl:1
	s_nop 1
	v_add_f32_dpp v18, v18, v18 quad_perm:[2,3,0,1] row_mask:0xf bank_mask:0xf bound_ctrl:1
	s_nop 1
	v_add_f32_dpp v18, v18, v18 row_ror:4 row_mask:0xf bank_mask:0xf bound_ctrl:1
	s_nop 1
	v_add_f32_dpp v18, v18, v18 row_ror:8 row_mask:0xf bank_mask:0xf bound_ctrl:1
	v_mov_b32_e32 v19, v18
	s_nop 1
	v_permlane16_swap_b32_e32 v18, v19
	s_and_saveexec_b64 s[20:21], s[2:3]
	v_add_f32_e32 v18, v18, v19
	ds_write_b32 v138, v18 offset:108
	s_or_b64 exec, exec, s[20:21]
	s_waitcnt vmcnt(19)
	v_mul_f32_e32 v15, v15, v137
	v_fmac_f32_e32 v15, v14, v135
	v_fmac_f32_e32 v15, v16, v136
	v_fmac_f32_e32 v15, v17, v134
	s_nop 1
	v_add_f32_dpp v14, v15, v15 quad_perm:[1,0,3,2] row_mask:0xf bank_mask:0xf bound_ctrl:1
	s_nop 1
	v_add_f32_dpp v14, v14, v14 quad_perm:[2,3,0,1] row_mask:0xf bank_mask:0xf bound_ctrl:1
	s_nop 1
	v_add_f32_dpp v14, v14, v14 row_ror:4 row_mask:0xf bank_mask:0xf bound_ctrl:1
	s_nop 1
	v_add_f32_dpp v14, v14, v14 row_ror:8 row_mask:0xf bank_mask:0xf bound_ctrl:1
	v_mov_b32_e32 v15, v14
	s_nop 1
	v_permlane16_swap_b32_e32 v14, v15
	s_and_saveexec_b64 s[20:21], s[2:3]
	v_add_f32_e32 v14, v14, v15
	ds_write_b32 v138, v14 offset:112
	s_or_b64 exec, exec, s[20:21]
	s_waitcnt vmcnt(18)
	v_mul_f32_e32 v11, v11, v137
	v_fmac_f32_e32 v11, v10, v135
	v_fmac_f32_e32 v11, v12, v136
	v_fmac_f32_e32 v11, v13, v134
	s_nop 1
	v_add_f32_dpp v10, v11, v11 quad_perm:[1,0,3,2] row_mask:0xf bank_mask:0xf bound_ctrl:1
	s_nop 1
	v_add_f32_dpp v10, v10, v10 quad_perm:[2,3,0,1] row_mask:0xf bank_mask:0xf bound_ctrl:1
	s_nop 1
	v_add_f32_dpp v10, v10, v10 row_ror:4 row_mask:0xf bank_mask:0xf bound_ctrl:1
	s_nop 1
	v_add_f32_dpp v10, v10, v10 row_ror:8 row_mask:0xf bank_mask:0xf bound_ctrl:1
	v_mov_b32_e32 v11, v10
	s_nop 1
	v_permlane16_swap_b32_e32 v10, v11
	s_and_saveexec_b64 s[20:21], s[2:3]
	v_add_f32_e32 v10, v10, v11
	ds_write_b32 v138, v10 offset:116
	s_or_b64 exec, exec, s[20:21]
	s_waitcnt vmcnt(17)
	v_mul_f32_e32 v7, v7, v137
	v_fmac_f32_e32 v7, v6, v135
	v_fmac_f32_e32 v7, v8, v136
	v_fmac_f32_e32 v7, v9, v134
	s_nop 1
	v_add_f32_dpp v6, v7, v7 quad_perm:[1,0,3,2] row_mask:0xf bank_mask:0xf bound_ctrl:1
	s_nop 1
	v_add_f32_dpp v6, v6, v6 quad_perm:[2,3,0,1] row_mask:0xf bank_mask:0xf bound_ctrl:1
	s_nop 1
	v_add_f32_dpp v6, v6, v6 row_ror:4 row_mask:0xf bank_mask:0xf bound_ctrl:1
	s_nop 1
	v_add_f32_dpp v6, v6, v6 row_ror:8 row_mask:0xf bank_mask:0xf bound_ctrl:1
	v_mov_b32_e32 v7, v6
	s_nop 1
	v_permlane16_swap_b32_e32 v6, v7
	s_and_saveexec_b64 s[20:21], s[2:3]
	v_add_f32_e32 v6, v6, v7
	ds_write_b32 v138, v6 offset:120
	s_or_b64 exec, exec, s[20:21]
	s_waitcnt vmcnt(16)
	v_mul_f32_e32 v3, v3, v137
	v_fmac_f32_e32 v3, v2, v135
	v_fmac_f32_e32 v3, v4, v136
	v_fmac_f32_e32 v3, v5, v134
	s_nop 1
	v_add_f32_dpp v2, v3, v3 quad_perm:[1,0,3,2] row_mask:0xf bank_mask:0xf bound_ctrl:1
	s_nop 1
	v_add_f32_dpp v2, v2, v2 quad_perm:[2,3,0,1] row_mask:0xf bank_mask:0xf bound_ctrl:1
	s_nop 1
	v_add_f32_dpp v2, v2, v2 row_ror:4 row_mask:0xf bank_mask:0xf bound_ctrl:1
	s_nop 1
	v_add_f32_dpp v2, v2, v2 row_ror:8 row_mask:0xf bank_mask:0xf bound_ctrl:1
	v_mov_b32_e32 v3, v2
	s_nop 1
	v_permlane16_swap_b32_e32 v2, v3
	s_and_saveexec_b64 s[20:21], s[2:3]
	v_add_f32_e32 v2, v2, v3
	ds_write_b32 v138, v2 offset:124
	s_or_b64 exec, exec, s[20:21]
	v_lshlrev_b32_e32 v134, 2, v132
	v_add_co_u32_e32 v2, vcc, 0x8000, v130
	s_nop 1
	v_addc_co_u32_e32 v3, vcc, 0, v131, vcc
	global_load_dwordx4 v[42:45], v[2:3], off offset:1024 nt
	global_load_dwordx4 v[38:41], v[2:3], off offset:3072 nt
	v_add_co_u32_e32 v2, vcc, 0x9000, v130
	s_nop 1
	v_addc_co_u32_e32 v3, vcc, 0, v131, vcc
	global_load_dwordx4 v[118:121], v[2:3], off offset:1024 nt
	global_load_dwordx4 v[110:113], v[2:3], off offset:3072 nt
	v_add_co_u32_e32 v2, vcc, 0xa000, v130
	s_nop 1
	v_addc_co_u32_e32 v3, vcc, 0, v131, vcc
	global_load_dwordx4 v[126:129], v[2:3], off offset:1024 nt
	global_load_dwordx4 v[114:117], v[2:3], off offset:3072 nt
	v_add_co_u32_e32 v2, vcc, 0xb000, v130
	s_nop 1
	v_addc_co_u32_e32 v3, vcc, 0, v131, vcc
	global_load_dwordx4 v[122:125], v[2:3], off offset:1024 nt
	global_load_dwordx4 v[34:37], v[2:3], off offset:3072 nt
	v_add_co_u32_e32 v2, vcc, 0xc000, v130
	s_nop 1
	v_addc_co_u32_e32 v3, vcc, 0, v131, vcc
	v_add_co_u32_e32 v6, vcc, 0xd000, v130
	global_load_dwordx4 v[10:13], v[2:3], off offset:1024 nt
	s_nop 0
	global_load_dwordx4 v[2:5], v[2:3], off offset:3072 nt
	v_addc_co_u32_e32 v7, vcc, 0, v131, vcc
	global_load_dwordx4 v[22:25], v[6:7], off offset:1024 nt
	global_load_dwordx4 v[14:17], v[6:7], off offset:3072 nt
	v_add_co_u32_e32 v6, vcc, 0xe000, v130
	s_nop 1
	v_addc_co_u32_e32 v7, vcc, 0, v131, vcc
	global_load_dwordx4 v[30:33], v[6:7], off offset:1024 nt
	global_load_dwordx4 v[18:21], v[6:7], off offset:3072 nt
	v_add_co_u32_e32 v6, vcc, 0xf000, v130
	s_nop 1
	v_addc_co_u32_e32 v7, vcc, 0, v131, vcc
	global_load_dwordx4 v[26:29], v[6:7], off offset:1024 nt
	s_nop 0
	global_load_dwordx4 v[6:9], v[6:7], off offset:3072 nt
	s_waitcnt lgkmcnt(0)
	s_barrier
	s_lshl_b32 s19, s43, 10
	s_cmp_gt_i32 s43, 1
	s_cbranch_scc1 .LBB0_880
	s_add_i32 s20, s19, 0
	v_lshl_add_u32 v135, v134, 2, s20
	ds_read_b128 v[136:139], v135
	v_cmp_eq_u32_e32 vcc, 0, v132
	s_waitcnt lgkmcnt(0)
	v_max_f32_e32 v130, v139, v139
	v_max_f32_e32 v131, v138, v138
	v_max_f32_e32 v130, v131, v130
	v_max3_f32 v130, v136, v137, v130
	s_nop 1
	v_mov_b32_dpp v131, v130 quad_perm:[1,0,3,2] row_mask:0xf bank_mask:0xf bound_ctrl:1
	v_max_f32_e32 v131, v131, v131
	v_max_f32_e32 v130, v130, v131
	s_nop 1
	v_mov_b32_dpp v131, v130 quad_perm:[2,3,0,1] row_mask:0xf bank_mask:0xf bound_ctrl:1
	v_max_f32_e32 v131, v131, v131
	v_max_f32_e32 v130, v130, v131
	s_nop 1
	v_mov_b32_dpp v131, v130 row_ror:4 row_mask:0xf bank_mask:0xf bound_ctrl:1
	v_max_f32_e32 v131, v131, v131
	v_max_f32_e32 v130, v130, v131
	s_nop 1
	v_mov_b32_dpp v131, v130 row_ror:8 row_mask:0xf bank_mask:0xf bound_ctrl:1
	v_max_f32_e32 v131, v131, v131
	v_max_f32_e32 v130, v130, v131
	v_mov_b32_e32 v131, v130
	s_nop 1
	v_permlane16_swap_b32_e32 v130, v131
	v_max_f32_e32 v131, v131, v131
	v_max_f32_e32 v130, v130, v130
	v_max_f32_e32 v130, v130, v131
	v_mov_b32_e32 v131, v130
	s_nop 1
	v_permlane32_swap_b32_e32 v130, v131
	v_max_f32_e32 v131, v131, v131
	v_max_f32_e32 v130, v130, v130
	v_max_f32_e32 v130, v130, v131
	v_sub_f32_e32 v131, v136, v130
	v_exp_f32_e32 v136, v131
	v_sub_f32_e32 v131, v137, v130
	v_exp_f32_e32 v137, v131
	v_sub_f32_e32 v131, v138, v130
	v_exp_f32_e32 v138, v131
	v_sub_f32_e32 v130, v139, v130
	v_exp_f32_e32 v139, v130
	v_add_f32_e32 v130, v136, v137
	v_add_f32_e32 v130, v138, v130
	v_add_f32_e32 v130, v139, v130
	ds_write_b128 v135, v[136:139]
	s_nop 0
	v_add_f32_dpp v130, v130, v130 quad_perm:[1,0,3,2] row_mask:0xf bank_mask:0xf bound_ctrl:1
	s_nop 1
	v_add_f32_dpp v130, v130, v130 quad_perm:[2,3,0,1] row_mask:0xf bank_mask:0xf bound_ctrl:1
	s_nop 1
	v_add_f32_dpp v130, v130, v130 row_ror:4 row_mask:0xf bank_mask:0xf bound_ctrl:1
	s_nop 1
	v_add_f32_dpp v130, v130, v130 row_ror:8 row_mask:0xf bank_mask:0xf bound_ctrl:1
	v_mov_b32_e32 v131, v130
	s_nop 1
	v_permlane16_swap_b32_e32 v130, v131
	v_add_f32_e32 v130, v130, v131
	v_mov_b32_e32 v131, v130
	s_nop 1
	v_permlane32_swap_b32_e32 v130, v131
	s_and_saveexec_b64 s[2:3], vcc
	s_cbranch_execz .LBB0_879
	v_add_f32_e32 v130, v130, v131
	v_div_scale_f32 v131, s[44:45], v130, v130, 1.0
	v_rcp_f32_e32 v132, v131
	v_div_scale_f32 v135, vcc, 1.0, v130, 1.0
	s_mulk_i32 s43, 0xfc04
	v_fma_f32 v136, -v131, v132, 1.0
	v_fmac_f32_e32 v132, v136, v132
	v_mul_f32_e32 v136, v135, v132
	v_fma_f32 v137, -v131, v136, v135
	v_fmac_f32_e32 v136, v137, v132
	v_fma_f32 v131, -v131, v136, v135
	v_div_fmas_f32 v131, v131, v132, v136
	s_add_i32 s20, s20, s43
	v_div_fixup_f32 v130, v131, v130, 1.0
	v_mov_b32_e32 v131, s20
	ds_write_b32 v131, v130 offset:2048
